# mix_c item loops (P4, P11, P12): the barrier closing each item moved onto the loop-exit edge (added to the rg change)
# baseline (speedup 1.0000x reference)
.Lmcx_p4:
	s_barrier
	s_branch .LBB0_596

.LBB0_783:
	s_or_b64 exec, exec, s[6:7]
	s_add_i32 s2, s50, s22
	s_lshl_b32 s6, s8, 2
	s_add_u32 s6, s38, s6
	s_addc_u32 s7, s39, 0
	s_waitcnt lgkmcnt(0)
	v_lshl_add_u64 v[76:77], v[74:75], 2, s[6:7]
	s_barrier
	global_load_dwordx4 v[248:251], v[76:77], off
	v_ashrrev_i32_e32 v95, 31, v94
	v_lshl_add_u32 v1, v144, 2, s96
	v_lshlrev_b64 v[96:97], 11, v[2:3]
	v_lshl_add_u32 v2, v73, 2, s96
	s_waitcnt vmcnt(4)
	v_lshlrev_b32_e32 v98, 16, v80
	v_and_b32_e32 v99, 0xffff0000, v80
	v_lshlrev_b32_e32 v100, 16, v81
	v_and_b32_e32 v101, 0xffff0000, v81
	ds_read2st64_b32 v[102:103], v1 offset1:1
	ds_read2st64_b32 v[104:105], v1 offset0:2 offset1:3
	ds_read2st64_b32 v[106:107], v1 offset0:4 offset1:5
	ds_read2st64_b32 v[108:109], v1 offset0:6 offset1:7
	v_lshlrev_b64 v[80:81], 1, v[94:95]
	ds_read2st64_b32 v[94:95], v2 offset1:1
	ds_read2st64_b32 v[110:111], v2 offset0:2 offset1:3
	ds_read2st64_b32 v[112:113], v2 offset0:4 offset1:5
	ds_read2st64_b32 v[114:115], v2 offset0:6 offset1:7
	s_waitcnt lgkmcnt(7)
	v_mov_b32_e32 v117, v102
	s_waitcnt lgkmcnt(3)
	v_mov_b32_e32 v116, v94
	v_mov_b32_e32 v102, v95
	v_pk_add_f32 v[116:117], v[116:117], 0 op_sel_hi:[1,0]
	s_waitcnt lgkmcnt(2)
	v_mov_b32_e32 v94, v110
	v_mov_b32_e32 v95, v104
	v_pk_add_f32 v[102:103], v[116:117], v[102:103]
	v_mov_b32_e32 v104, v111
	v_pk_add_f32 v[94:95], v[102:103], v[94:95]
	v_mul_f32_e32 v1, 0xbfb8aa3b, v98
	s_waitcnt lgkmcnt(1)
	v_mov_b32_e32 v110, v112
	v_mov_b32_e32 v111, v106
	v_pk_add_f32 v[94:95], v[94:95], v[104:105]
	v_exp_f32_e32 v1, v1
	v_mov_b32_e32 v106, v113
	v_pk_add_f32 v[94:95], v[94:95], v[110:111]
	s_waitcnt lgkmcnt(0)
	v_mov_b32_e32 v112, v114
	v_mov_b32_e32 v113, v108
	v_pk_add_f32 v[94:95], v[94:95], v[106:107]
	v_mov_b32_e32 v108, v115
	v_pk_add_f32 v[94:95], v[94:95], v[112:113]
	v_mov_b64_e32 v[86:87], s[82:83]
	v_pk_add_f32 v[94:95], v[94:95], v[108:109]
	v_mul_f32_e32 v61, 0xbfb8aa3b, v99
	v_mul_f32_e32 v73, 0xbfb8aa3b, v100
	v_mul_f32_e32 v83, 0xbfb8aa3b, v101
	v_add_f32_e32 v1, 1.0, v1
	v_pk_fma_f32 v[94:95], v[94:95], s[80:81], v[86:87] op_sel_hi:[1,0,0]
	v_exp_f32_e32 v2, v61
	v_exp_f32_e32 v61, v73
	v_exp_f32_e32 v73, v83
	v_rcp_f32_e32 v114, v1
	v_mul_f32_e32 v1, 0x4b800000, v95
	v_cmp_gt_f32_e32 vcc, s42, v95
	v_add_f32_e32 v2, 1.0, v2
	v_add_f32_e32 v61, 1.0, v61
	v_cndmask_b32_e32 v1, v95, v1, vcc
	v_rsq_f32_e32 v1, v1
	v_add_f32_e32 v73, 1.0, v73
	v_rcp_f32_e32 v115, v2
	v_rcp_f32_e32 v118, v61
	v_rcp_f32_e32 v119, v73
	v_mul_f32_e32 v2, 0x45800000, v1
	v_cndmask_b32_e32 v2, v1, v2, vcc
	v_lshl_add_u64 v[96:97], s[16:17], 0, v[96:97]
	v_pk_mul_f32 v[68:69], v[68:69], v[2:3] op_sel_hi:[1,0]
	v_pk_mul_f32 v[70:71], v[70:71], v[2:3] op_sel_hi:[1,0]
	v_lshl_add_u64 v[96:97], v[96:97], 0, s[62:63]
	v_pk_mul_f32 v[98:99], v[114:115], v[98:99]
	v_pk_mul_f32 v[100:101], v[118:119], v[100:101]
	v_lshlrev_b32_e32 v74, 1, v150
	v_mov_b32_e32 v75, v0
	v_lshl_add_u64 v[96:97], v[96:97], 0, v[80:81]
	v_lshl_add_u64 v[96:97], v[96:97], 0, v[74:75]
	v_cmp_gt_f32_e32 vcc, s42, v94
	v_mov_b32_e32 v83, v3
	v_lshlrev_b64 v[82:83], 11, v[82:83]
	v_lshl_add_u64 v[82:83], s[16:17], 0, v[82:83]
	v_lshl_add_u64 v[82:83], v[82:83], 0, s[62:63]
	v_lshl_add_u64 v[82:83], v[82:83], 0, v[80:81]
	v_lshl_add_u64 v[82:83], v[82:83], 0, v[74:75]
	s_add_i32 s73, s73, s88
	s_add_i32 s61, s61, s91
	s_cmpk_gt_i32 s2, 0x7ff
	s_cselect_b64 s[6:7], -1, 0
	s_waitcnt vmcnt(0)
	v_pk_mul_f32 v[68:69], v[248:249], v[68:69]
	v_pk_mul_f32 v[70:71], v[250:251], v[70:71]
	v_pk_mul_f32 v[68:69], v[98:99], v[68:69]
	v_pk_mul_f32 v[70:71], v[100:101], v[70:71]
	v_cvt_pk_bf16_f32 v68, v68, v69
	v_cvt_pk_bf16_f32 v69, v70, v71
	global_store_dwordx2 v[96:97], v[68:69], off offset:1024
	s_nop 0
	v_lshlrev_b32_e32 v90, 16, v84
	v_mul_f32_e32 v1, 0xbfb8aa3b, v90
	v_exp_f32_e32 v1, v1
	v_and_b32_e32 v91, 0xffff0000, v84
	v_lshlrev_b32_e32 v84, 16, v85
	v_and_b32_e32 v85, 0xffff0000, v85
	v_mul_f32_e32 v2, 0xbfb8aa3b, v91
	v_mul_f32_e32 v61, 0xbfb8aa3b, v84
	v_mul_f32_e32 v73, 0xbfb8aa3b, v85
	v_add_f32_e32 v1, 1.0, v1
	v_exp_f32_e32 v2, v2
	v_exp_f32_e32 v61, v61
	v_exp_f32_e32 v73, v73
	v_rcp_f32_e32 v92, v1
	v_mul_f32_e32 v1, 0x4b800000, v94
	v_cndmask_b32_e32 v1, v94, v1, vcc
	v_rsq_f32_e32 v1, v1
	v_add_f32_e32 v2, 1.0, v2
	v_add_f32_e32 v61, 1.0, v61
	v_add_f32_e32 v73, 1.0, v73
	v_rcp_f32_e32 v93, v2
	v_rcp_f32_e32 v96, v61
	v_rcp_f32_e32 v97, v73
	v_mul_f32_e32 v2, 0x45800000, v1
	v_cndmask_b32_e32 v2, v1, v2, vcc
	v_pk_mul_f32 v[64:65], v[64:65], v[2:3] op_sel_hi:[1,0]
	v_pk_mul_f32 v[66:67], v[66:67], v[2:3] op_sel_hi:[1,0]
	v_pk_mul_f32 v[90:91], v[92:93], v[90:91]
	v_pk_mul_f32 v[84:85], v[96:97], v[84:85]
	v_lshl_add_u32 v1, v89, 2, s96
	v_lshl_add_u32 v2, v88, 2, s96
	v_mov_b32_e32 v73, v3
	v_lshlrev_b64 v[72:73], 11, v[72:73]
	v_lshl_add_u64 v[72:73], s[16:17], 0, v[72:73]
	v_lshl_add_u64 v[72:73], v[72:73], 0, s[62:63]
	v_lshl_add_u64 v[72:73], v[72:73], 0, v[80:81]
	v_lshl_add_u64 v[72:73], v[72:73], 0, v[74:75]
	s_nop 0
	v_pk_mul_f32 v[64:65], v[248:249], v[64:65]
	v_pk_mul_f32 v[66:67], v[250:251], v[66:67]
	v_pk_mul_f32 v[64:65], v[90:91], v[64:65]
	v_pk_mul_f32 v[66:67], v[84:85], v[66:67]
	v_cvt_pk_bf16_f32 v64, v64, v65
	v_cvt_pk_bf16_f32 v65, v66, v67
	global_store_dwordx2 v[82:83], v[64:65], off offset:1024
	s_nop 0
	v_and_b32_e32 v69, 0xffff0000, v78
	v_lshlrev_b32_e32 v70, 16, v79
	v_and_b32_e32 v71, 0xffff0000, v79
	v_mul_f32_e32 v61, 0xbfb8aa3b, v69
	v_mul_f32_e32 v98, 0xbfb8aa3b, v70
	v_mul_f32_e32 v99, 0xbfb8aa3b, v71
	v_lshlrev_b32_e32 v68, 16, v78
	ds_read2st64_b32 v[78:79], v1 offset1:1
	ds_read2st64_b32 v[82:83], v1 offset0:2 offset1:3
	ds_read2st64_b32 v[84:85], v1 offset0:4 offset1:5
	ds_read2st64_b32 v[88:89], v1 offset0:6 offset1:7
	ds_read2st64_b32 v[90:91], v2 offset1:1
	ds_read2st64_b32 v[92:93], v2 offset0:2 offset1:3
	ds_read2st64_b32 v[94:95], v2 offset0:4 offset1:5
	ds_read2st64_b32 v[96:97], v2 offset0:6 offset1:7
	v_exp_f32_e32 v2, v61
	v_exp_f32_e32 v61, v98
	v_exp_f32_e32 v98, v99
	s_waitcnt lgkmcnt(7)
	v_mov_b32_e32 v99, v78
	s_waitcnt lgkmcnt(3)
	v_mov_b32_e32 v78, v91
	v_mov_b32_e32 v91, v82
	v_add_f32_e32 v101, 1.0, v98
	v_mov_b32_e32 v98, v90
	v_pk_add_f32 v[98:99], v[98:99], 0 op_sel_hi:[1,0]
	s_waitcnt lgkmcnt(2)
	v_mov_b32_e32 v90, v92
	v_pk_add_f32 v[78:79], v[98:99], v[78:79]
	v_mov_b32_e32 v82, v93
	v_pk_add_f32 v[78:79], v[78:79], v[90:91]
	v_mul_f32_e32 v1, 0xbfb8aa3b, v68
	s_waitcnt lgkmcnt(1)
	v_mov_b32_e32 v92, v94
	v_mov_b32_e32 v93, v84
	v_pk_add_f32 v[78:79], v[78:79], v[82:83]
	v_exp_f32_e32 v1, v1
	v_mov_b32_e32 v84, v95
	v_pk_add_f32 v[78:79], v[78:79], v[92:93]
	s_waitcnt lgkmcnt(0)
	v_mov_b32_e32 v94, v96
	v_mov_b32_e32 v95, v88
	v_pk_add_f32 v[78:79], v[78:79], v[84:85]
	v_mov_b32_e32 v88, v97
	v_pk_add_f32 v[78:79], v[78:79], v[94:95]
	v_add_f32_e32 v1, 1.0, v1
	v_pk_add_f32 v[78:79], v[78:79], v[88:89]
	v_rcp_f32_e32 v96, v1
	v_pk_fma_f32 v[78:79], v[78:79], s[80:81], v[86:87] op_sel_hi:[1,0,0]
	v_add_f32_e32 v2, 1.0, v2
	v_mul_f32_e32 v1, 0x4b800000, v79
	v_cmp_gt_f32_e32 vcc, s42, v79
	v_add_f32_e32 v61, 1.0, v61
	v_rcp_f32_e32 v97, v2
	v_cndmask_b32_e32 v1, v79, v1, vcc
	v_rsq_f32_e32 v1, v1
	v_rcp_f32_e32 v100, v61
	v_rcp_f32_e32 v101, v101
	v_pk_mul_f32 v[68:69], v[96:97], v[68:69]
	v_mul_f32_e32 v2, 0x45800000, v1
	v_cndmask_b32_e32 v2, v1, v2, vcc
	v_pk_mul_f32 v[56:57], v[56:57], v[2:3] op_sel_hi:[1,0]
	v_pk_mul_f32 v[58:59], v[58:59], v[2:3] op_sel_hi:[1,0]
	v_pk_mul_f32 v[70:71], v[100:101], v[70:71]
	v_lshlrev_b32_e32 v2, 16, v62
	v_mov_b32_e32 v61, v3
	v_and_b32_e32 v3, 0xffff0000, v62
	v_mul_f32_e32 v1, 0xbfb8aa3b, v2
	v_exp_f32_e32 v1, v1
	v_lshlrev_b32_e32 v62, 16, v63
	v_and_b32_e32 v63, 0xffff0000, v63
	v_cmp_gt_f32_e32 vcc, s42, v78
	v_add_f32_e32 v1, 1.0, v1
	v_lshlrev_b64 v[60:61], 11, v[60:61]
	v_lshl_add_u64 v[60:61], s[16:17], 0, v[60:61]
	v_lshl_add_u64 v[60:61], v[60:61], 0, s[62:63]
	v_lshl_add_u64 v[60:61], v[60:61], 0, v[80:81]
	v_lshl_add_u64 v[60:61], v[60:61], 0, v[74:75]
	s_nop 0
	v_pk_mul_f32 v[56:57], v[248:249], v[56:57]
	v_pk_mul_f32 v[58:59], v[250:251], v[58:59]
	v_pk_mul_f32 v[56:57], v[68:69], v[56:57]
	v_pk_mul_f32 v[58:59], v[70:71], v[58:59]
	v_cvt_pk_bf16_f32 v56, v56, v57
	v_cvt_pk_bf16_f32 v57, v58, v59
	global_store_dwordx2 v[72:73], v[56:57], off offset:1024
	s_nop 0
	v_mul_f32_e32 v64, 0xbfb8aa3b, v3
	v_exp_f32_e32 v64, v64
	v_mul_f32_e32 v65, 0xbfb8aa3b, v62
	v_exp_f32_e32 v65, v65
	v_mul_f32_e32 v66, 0xbfb8aa3b, v63
	v_exp_f32_e32 v66, v66
	v_add_f32_e32 v67, 1.0, v64
	v_rcp_f32_e32 v64, v1
	v_mul_f32_e32 v1, 0x4b800000, v78
	v_cndmask_b32_e32 v1, v78, v1, vcc
	v_add_f32_e32 v68, 1.0, v65
	v_rcp_f32_e32 v65, v67
	v_rsq_f32_e32 v1, v1
	v_add_f32_e32 v69, 1.0, v66
	v_rcp_f32_e32 v66, v68
	v_rcp_f32_e32 v67, v69
	v_pk_mul_f32 v[2:3], v[64:65], v[2:3]
	v_mul_f32_e32 v64, 0x45800000, v1
	v_cndmask_b32_e32 v64, v1, v64, vcc
	v_pk_mul_f32 v[52:53], v[52:53], v[64:65] op_sel_hi:[1,0]
	v_pk_mul_f32 v[54:55], v[54:55], v[64:65] op_sel_hi:[1,0]
	v_pk_mul_f32 v[62:63], v[66:67], v[62:63]
	s_nop 0
	v_pk_mul_f32 v[52:53], v[248:249], v[52:53]
	v_pk_mul_f32 v[54:55], v[250:251], v[54:55]
	v_pk_mul_f32 v[2:3], v[2:3], v[52:53]
	v_pk_mul_f32 v[52:53], v[62:63], v[54:55]
	v_cvt_pk_bf16_f32 v2, v2, v3
	v_cvt_pk_bf16_f32 v3, v52, v53
	global_store_dwordx2 v[60:61], v[2:3], off offset:1024
	s_nop 0

.LBB0_805:
	s_or_b64 exec, exec, s[6:7]
	s_lshl_b32 s6, s8, 2
	s_add_u32 s6, s38, s6
	s_addc_u32 s7, s39, 0
	v_lshl_add_u64 v[78:79], v[78:79], 2, s[6:7]
	s_waitcnt lgkmcnt(0)
	s_barrier
	global_load_dwordx4 v[248:251], v[78:79], off
	v_ashrrev_i32_e32 v93, 31, v92
	v_lshl_add_u32 v61, v144, 2, s96
	v_lshlrev_b64 v[84:85], 11, v[2:3]
	v_lshl_add_u32 v2, v73, 2, s96
	s_waitcnt vmcnt(4)
	v_lshlrev_b32_e32 v90, 16, v76
	v_and_b32_e32 v91, 0xffff0000, v76
	v_lshlrev_b32_e32 v98, 16, v77
	v_and_b32_e32 v99, 0xffff0000, v77
	ds_read2st64_b32 v[100:101], v61 offset1:1
	ds_read2st64_b32 v[102:103], v61 offset0:2 offset1:3
	ds_read2st64_b32 v[104:105], v61 offset0:4 offset1:5
	ds_read2st64_b32 v[106:107], v61 offset0:6 offset1:7
	v_lshl_add_u64 v[108:109], s[16:17], 0, v[84:85]
	v_lshlrev_b64 v[84:85], 1, v[92:93]
	ds_read2st64_b32 v[92:93], v2 offset1:1
	ds_read2st64_b32 v[110:111], v2 offset0:2 offset1:3
	ds_read2st64_b32 v[112:113], v2 offset0:4 offset1:5
	ds_read2st64_b32 v[114:115], v2 offset0:6 offset1:7
	v_mul_f32_e32 v61, 0xbfb8aa3b, v90
	v_mul_f32_e32 v73, 0xbfb8aa3b, v91
	v_mul_f32_e32 v81, 0xbfb8aa3b, v98
	v_mul_f32_e32 v116, 0xbfb8aa3b, v99
	v_exp_f32_e32 v2, v61
	v_exp_f32_e32 v61, v73
	v_exp_f32_e32 v73, v81
	v_exp_f32_e32 v81, v116
	s_waitcnt lgkmcnt(3)
	v_mov_b32_e32 v116, v92
	v_mov_b32_e32 v117, v100
	v_mov_b32_e32 v100, v93
	v_pk_add_f32 v[116:117], v[116:117], 0 op_sel_hi:[1,0]
	s_waitcnt lgkmcnt(2)
	v_mov_b32_e32 v92, v110
	v_mov_b32_e32 v93, v102
	v_pk_add_f32 v[100:101], v[116:117], v[100:101]
	v_mov_b32_e32 v102, v111
	v_pk_add_f32 v[92:93], v[100:101], v[92:93]
	s_waitcnt lgkmcnt(1)
	v_mov_b32_e32 v110, v112
	v_mov_b32_e32 v111, v104
	v_pk_add_f32 v[92:93], v[92:93], v[102:103]
	v_mov_b32_e32 v104, v113
	v_pk_add_f32 v[92:93], v[92:93], v[110:111]
	s_waitcnt lgkmcnt(0)
	v_mov_b32_e32 v112, v114
	v_mov_b32_e32 v113, v106
	v_pk_add_f32 v[92:93], v[92:93], v[104:105]
	v_mov_b32_e32 v106, v115
	v_pk_add_f32 v[92:93], v[92:93], v[112:113]
	v_mov_b64_e32 v[86:87], s[82:83]
	v_pk_add_f32 v[92:93], v[92:93], v[106:107]
	v_add_f32_e32 v2, 1.0, v2
	v_pk_fma_f32 v[92:93], v[92:93], s[80:81], v[86:87] op_sel_hi:[1,0,0]
	v_rcp_f32_e32 v114, v2
	v_mul_f32_e32 v2, 0x4b800000, v93
	v_cmp_gt_f32_e32 vcc, s42, v93
	v_add_f32_e32 v61, 1.0, v61
	v_add_f32_e32 v73, 1.0, v73
	v_cndmask_b32_e32 v2, v93, v2, vcc
	v_rsq_f32_e32 v2, v2
	v_add_f32_e32 v81, 1.0, v81
	v_rcp_f32_e32 v115, v61
	v_rcp_f32_e32 v118, v73
	v_rcp_f32_e32 v119, v81
	v_mul_f32_e32 v61, 0x45800000, v2
	v_cndmask_b32_e32 v2, v2, v61, vcc
	v_pk_mul_f32 v[68:69], v[68:69], v[2:3] op_sel_hi:[1,0]
	v_pk_mul_f32 v[70:71], v[70:71], v[2:3] op_sel_hi:[1,0]
	v_lshl_add_u64 v[108:109], v[108:109], 0, s[62:63]
	v_pk_mul_f32 v[90:91], v[114:115], v[90:91]
	v_pk_mul_f32 v[98:99], v[118:119], v[98:99]
	v_lshlrev_b32_e32 v76, 1, v145
	v_mov_b32_e32 v77, v0
	v_lshl_add_u64 v[108:109], v[108:109], 0, v[84:85]
	v_lshl_add_u64 v[100:101], v[108:109], 0, v[76:77]
	v_cmp_gt_f32_e32 vcc, s42, v92
	v_mov_b32_e32 v81, v3
	v_lshlrev_b64 v[80:81], 11, v[80:81]
	v_lshl_add_u64 v[80:81], s[16:17], 0, v[80:81]
	v_lshl_add_u64 v[80:81], v[80:81], 0, s[62:63]
	v_lshl_add_u64 v[80:81], v[80:81], 0, v[84:85]
	v_lshl_add_u64 v[80:81], v[80:81], 0, v[76:77]
	s_cmpk_gt_i32 s50, 0x7ff
	s_mov_b64 s[6:7], -1
	s_waitcnt vmcnt(0)
	v_pk_mul_f32 v[68:69], v[248:249], v[68:69]
	v_pk_mul_f32 v[70:71], v[250:251], v[70:71]
	v_pk_mul_f32 v[68:69], v[90:91], v[68:69]
	v_pk_mul_f32 v[70:71], v[98:99], v[70:71]
	v_cvt_pk_bf16_f32 v68, v68, v69
	v_cvt_pk_bf16_f32 v69, v70, v71
	global_store_dwordx2 v[100:101], v[68:69], off offset:1024
	s_nop 0
	v_lshlrev_b32_e32 v90, 16, v82
	v_mul_f32_e32 v2, 0xbfb8aa3b, v90
	v_exp_f32_e32 v2, v2
	v_and_b32_e32 v91, 0xffff0000, v82
	v_lshlrev_b32_e32 v82, 16, v83
	v_and_b32_e32 v83, 0xffff0000, v83
	v_mul_f32_e32 v61, 0xbfb8aa3b, v91
	v_mul_f32_e32 v73, 0xbfb8aa3b, v82
	v_mul_f32_e32 v93, 0xbfb8aa3b, v83
	v_add_f32_e32 v2, 1.0, v2
	v_exp_f32_e32 v61, v61
	v_exp_f32_e32 v73, v73
	v_exp_f32_e32 v93, v93
	v_rcp_f32_e32 v94, v2
	v_mul_f32_e32 v2, 0x4b800000, v92
	v_cndmask_b32_e32 v2, v92, v2, vcc
	v_rsq_f32_e32 v2, v2
	v_add_f32_e32 v61, 1.0, v61
	v_add_f32_e32 v73, 1.0, v73
	v_add_f32_e32 v93, 1.0, v93
	v_rcp_f32_e32 v95, v61
	v_rcp_f32_e32 v96, v73
	v_rcp_f32_e32 v97, v93
	v_mul_f32_e32 v61, 0x45800000, v2
	v_cndmask_b32_e32 v2, v2, v61, vcc
	v_pk_mul_f32 v[64:65], v[64:65], v[2:3] op_sel_hi:[1,0]
	v_pk_mul_f32 v[66:67], v[66:67], v[2:3] op_sel_hi:[1,0]
	v_pk_mul_f32 v[90:91], v[94:95], v[90:91]
	v_pk_mul_f32 v[82:83], v[96:97], v[82:83]
	v_lshl_add_u32 v2, v89, 2, s96
	v_lshl_add_u32 v61, v88, 2, s96
	v_mov_b32_e32 v73, v3
	v_lshlrev_b64 v[72:73], 11, v[72:73]
	v_lshl_add_u64 v[72:73], s[16:17], 0, v[72:73]
	v_lshl_add_u64 v[72:73], v[72:73], 0, s[62:63]
	v_lshl_add_u64 v[72:73], v[72:73], 0, v[84:85]
	v_lshl_add_u64 v[72:73], v[72:73], 0, v[76:77]
	s_nop 0
	v_pk_mul_f32 v[64:65], v[248:249], v[64:65]
	v_pk_mul_f32 v[66:67], v[250:251], v[66:67]
	v_pk_mul_f32 v[64:65], v[90:91], v[64:65]
	v_pk_mul_f32 v[66:67], v[82:83], v[66:67]
	v_cvt_pk_bf16_f32 v64, v64, v65
	v_cvt_pk_bf16_f32 v65, v66, v67
	global_store_dwordx2 v[80:81], v[64:65], off offset:1024
	s_nop 0
	v_and_b32_e32 v69, 0xffff0000, v74
	v_lshlrev_b32_e32 v70, 16, v75
	v_and_b32_e32 v71, 0xffff0000, v75
	v_mul_f32_e32 v98, 0xbfb8aa3b, v69
	v_mul_f32_e32 v99, 0xbfb8aa3b, v70
	v_mul_f32_e32 v100, 0xbfb8aa3b, v71
	v_lshlrev_b32_e32 v68, 16, v74
	ds_read2st64_b32 v[74:75], v2 offset1:1
	ds_read2st64_b32 v[80:81], v2 offset0:2 offset1:3
	ds_read2st64_b32 v[82:83], v2 offset0:4 offset1:5
	ds_read2st64_b32 v[88:89], v2 offset0:6 offset1:7
	ds_read2st64_b32 v[90:91], v61 offset1:1
	ds_read2st64_b32 v[92:93], v61 offset0:2 offset1:3
	ds_read2st64_b32 v[94:95], v61 offset0:4 offset1:5
	ds_read2st64_b32 v[96:97], v61 offset0:6 offset1:7
	v_exp_f32_e32 v61, v98
	v_exp_f32_e32 v98, v99
	v_exp_f32_e32 v99, v100
	v_mul_f32_e32 v2, 0xbfb8aa3b, v68
	v_exp_f32_e32 v2, v2
	v_add_f32_e32 v100, 1.0, v98
	v_add_f32_e32 v101, 1.0, v99
	s_waitcnt lgkmcnt(3)
	v_mov_b32_e32 v98, v90
	v_mov_b32_e32 v99, v74
	v_mov_b32_e32 v74, v91
	v_pk_add_f32 v[98:99], v[98:99], 0 op_sel_hi:[1,0]
	s_waitcnt lgkmcnt(2)
	v_mov_b32_e32 v90, v92
	v_mov_b32_e32 v91, v80
	v_pk_add_f32 v[74:75], v[98:99], v[74:75]
	v_mov_b32_e32 v80, v93
	v_pk_add_f32 v[74:75], v[74:75], v[90:91]
	s_waitcnt lgkmcnt(1)
	v_mov_b32_e32 v92, v94
	v_mov_b32_e32 v93, v82
	v_pk_add_f32 v[74:75], v[74:75], v[80:81]
	v_mov_b32_e32 v82, v95
	v_pk_add_f32 v[74:75], v[74:75], v[92:93]
	s_waitcnt lgkmcnt(0)
	v_mov_b32_e32 v94, v96
	v_mov_b32_e32 v95, v88
	v_pk_add_f32 v[74:75], v[74:75], v[82:83]
	v_mov_b32_e32 v88, v97
	v_pk_add_f32 v[74:75], v[74:75], v[94:95]
	v_add_f32_e32 v2, 1.0, v2
	v_pk_add_f32 v[74:75], v[74:75], v[88:89]
	v_rcp_f32_e32 v96, v2
	v_pk_fma_f32 v[74:75], v[74:75], s[80:81], v[86:87] op_sel_hi:[1,0,0]
	v_add_f32_e32 v61, 1.0, v61
	v_mul_f32_e32 v2, 0x4b800000, v75
	v_cmp_gt_f32_e32 vcc, s42, v75
	v_rcp_f32_e32 v97, v61
	v_rcp_f32_e32 v100, v100
	v_cndmask_b32_e32 v2, v75, v2, vcc
	v_rsq_f32_e32 v2, v2
	v_rcp_f32_e32 v101, v101
	v_pk_mul_f32 v[68:69], v[96:97], v[68:69]
	v_mul_f32_e32 v61, 0x45800000, v2
	v_cndmask_b32_e32 v2, v2, v61, vcc
	v_pk_mul_f32 v[56:57], v[56:57], v[2:3] op_sel_hi:[1,0]
	v_pk_mul_f32 v[58:59], v[58:59], v[2:3] op_sel_hi:[1,0]
	v_pk_mul_f32 v[70:71], v[100:101], v[70:71]
	v_mov_b32_e32 v61, v3
	v_lshlrev_b32_e32 v2, 16, v62
	v_and_b32_e32 v3, 0xffff0000, v62
	v_lshlrev_b32_e32 v62, 16, v63
	v_and_b32_e32 v63, 0xffff0000, v63
	v_cmp_gt_f32_e32 vcc, s42, v74
	v_lshlrev_b64 v[60:61], 11, v[60:61]
	v_lshl_add_u64 v[60:61], s[16:17], 0, v[60:61]
	v_lshl_add_u64 v[60:61], v[60:61], 0, s[62:63]
	v_lshl_add_u64 v[60:61], v[60:61], 0, v[84:85]
	v_lshl_add_u64 v[60:61], v[60:61], 0, v[76:77]
	s_nop 0
	v_pk_mul_f32 v[56:57], v[248:249], v[56:57]
	v_pk_mul_f32 v[58:59], v[250:251], v[58:59]
	v_pk_mul_f32 v[56:57], v[68:69], v[56:57]
	v_pk_mul_f32 v[58:59], v[70:71], v[58:59]
	v_cvt_pk_bf16_f32 v56, v56, v57
	v_cvt_pk_bf16_f32 v57, v58, v59
	global_store_dwordx2 v[72:73], v[56:57], off offset:1024
	s_nop 0
	v_mul_f32_e32 v64, 0xbfb8aa3b, v2
	v_mul_f32_e32 v65, 0xbfb8aa3b, v3
	v_exp_f32_e32 v64, v64
	v_exp_f32_e32 v65, v65
	v_mul_f32_e32 v66, 0xbfb8aa3b, v62
	v_mul_f32_e32 v67, 0xbfb8aa3b, v63
	v_exp_f32_e32 v66, v66
	v_exp_f32_e32 v67, v67
	v_mul_f32_e32 v68, 0x4b800000, v74
	v_add_f32_e32 v64, 1.0, v64
	v_add_f32_e32 v65, 1.0, v65
	v_cndmask_b32_e32 v68, v74, v68, vcc
	v_rcp_f32_e32 v64, v64
	v_rcp_f32_e32 v65, v65
	v_rsq_f32_e32 v68, v68
	v_add_f32_e32 v66, 1.0, v66
	v_add_f32_e32 v67, 1.0, v67
	v_rcp_f32_e32 v66, v66
	v_rcp_f32_e32 v67, v67
	v_pk_mul_f32 v[2:3], v[64:65], v[2:3]
	v_mul_f32_e32 v64, 0x45800000, v68
	v_cndmask_b32_e32 v64, v68, v64, vcc
	v_pk_mul_f32 v[52:53], v[52:53], v[64:65] op_sel_hi:[1,0]
	v_pk_mul_f32 v[54:55], v[54:55], v[64:65] op_sel_hi:[1,0]
	v_pk_mul_f32 v[62:63], v[66:67], v[62:63]
	s_nop 0
	v_pk_mul_f32 v[52:53], v[248:249], v[52:53]
	v_pk_mul_f32 v[54:55], v[250:251], v[54:55]
	v_pk_mul_f32 v[2:3], v[2:3], v[52:53]
	v_pk_mul_f32 v[52:53], v[62:63], v[54:55]
	v_cvt_pk_bf16_f32 v2, v2, v3
	v_cvt_pk_bf16_f32 v3, v52, v53
	global_store_dwordx2 v[60:61], v[2:3], off offset:1024
	s_nop 0
	s_cbranch_scc1 .LBB0_784
	s_add_i32 s2, s89, s2
	s_cmpk_gt_i32 s2, 0x7ff
	s_cbranch_scc1 .LBB0_808
	v_mov_b32_e32 v12, v204
	s_ashr_i32 s6, s2, 8
	v_ashrrev_i32_e32 v2, 31, v12
	v_lshrrev_b32_e32 v2, 28, v2
	v_add_u32_e32 v3, v12, v2
	s_ashr_i32 s7, s6, 31
	s_add_i32 s2, s88, s73
	v_ashrrev_i32_e32 v2, 4, v3
	v_and_b32_e32 v3, 0x1ffffff0, v3
	s_lshl_b64 s[6:7], s[6:7], 12
	s_and_b32 s2, s2, 0xfc0
	v_sub_u32_e32 v3, v12, v3
	s_or_b32 s6, s6, s2
	v_lshlrev_b32_e32 v4, 3, v3
	v_ashrrev_i32_e32 v3, 31, v2
	s_add_i32 s2, s91, s61
	v_lshl_add_u64 v[2:3], s[6:7], 0, v[2:3]
	v_mov_b64_e32 v[6:7], s[66:67]
	s_and_b32 s2, s2, 0x180
	v_mad_u64_u32 v[8:9], s[8:9], v2, s0, v[6:7]
	v_mad_i32_i24 v9, v3, s0, v9
	s_lshl_b32 s62, s2, 1
	v_lshl_add_u64 v[2:3], v[8:9], 0, s[62:63]
	v_ashrrev_i32_e32 v5, 31, v4
	v_lshl_add_u64 v[2:3], v[4:5], 1, v[2:3]
	v_add_u32_e32 v5, 0x200, v12
	v_ashrrev_i32_e32 v4, 31, v5
	v_lshrrev_b32_e32 v4, 28, v4
	v_add_u32_e32 v8, v5, v4
	v_ashrrev_i32_e32 v4, 4, v8
	v_and_b32_e32 v8, 0x1ffffff0, v8
	v_sub_u32_e32 v5, v5, v8
	v_lshlrev_b32_e32 v8, 3, v5
	v_ashrrev_i32_e32 v5, 31, v4
	v_lshl_add_u64 v[4:5], s[6:7], 0, v[4:5]
	v_mad_u64_u32 v[6:7], s[8:9], v4, s0, v[6:7]
	v_mad_i32_i24 v7, v5, s0, v7
	v_add_co_u32_e32 v2, vcc, s48, v2
	v_lshl_add_u64 v[4:5], v[6:7], 0, s[62:63]
	v_ashrrev_i32_e32 v9, 31, v8
	v_addc_co_u32_e32 v3, vcc, 0, v3, vcc
	v_lshl_add_u64 v[4:5], v[8:9], 1, v[4:5]
	v_add_co_u32_e32 v8, vcc, s48, v4
	s_add_u32 s8, s66, s62
	s_nop 0
	v_addc_co_u32_e32 v9, vcc, 0, v5, vcc
	global_load_dwordx4 v[4:7], v[2:3], off offset:1024
	s_nop 0
	global_load_dwordx4 v[8:11], v[8:9], off offset:1024
	v_ashrrev_i32_e32 v2, 4, v12
	v_lshlrev_b32_e32 v3, 4, v12
	s_addc_u32 s9, s67, 0
	v_and_b32_e32 v12, 0xf0, v3
	v_mov_b32_e32 v13, v0
	v_ashrrev_i32_e32 v3, 31, v2
	v_lshl_add_u64 v[12:13], s[8:9], 0, v[12:13]
	v_lshl_add_u64 v[14:15], s[6:7], 0, v[2:3]
	v_add_u32_e32 v2, 32, v2
	v_mad_u64_u32 v[20:21], s[8:9], v14, s0, v[12:13]
	v_ashrrev_i32_e32 v3, 31, v2
	v_mad_i32_i24 v21, v15, s0, v21
	v_add_co_u32_e32 v28, vcc, s48, v20
	v_lshl_add_u64 v[2:3], s[6:7], 0, v[2:3]
	s_nop 0
	v_addc_co_u32_e32 v29, vcc, 0, v21, vcc
	v_mad_u64_u32 v[30:31], s[6:7], v2, s0, v[12:13]
	v_mad_i32_i24 v31, v3, s0, v31
	v_add_co_u32_e32 v2, vcc, 0x1000, v30
	global_load_dwordx4 v[12:15], v[20:21], off offset:3072
	s_nop 0
	global_load_dwordx4 v[20:23], v[30:31], off offset:3072
	v_addc_co_u32_e32 v3, vcc, 0, v31, vcc
	global_load_dwordx4 v[28:31], v[28:29], off
	s_nop 0
	global_load_dwordx4 v[32:35], v[2:3], off

.LBB0_1594:
	s_or_b64 exec, exec, s[12:13]
	s_add_i32 s82, s81, s61
	s_lshl_b32 s12, s2, 2
	s_add_u32 s12, s26, s12
	s_addc_u32 s13, s27, 0
	v_lshl_add_u32 v0, v131, 2, s96
	v_lshl_add_u64 v[84:85], v[84:85], 2, s[12:13]
	s_waitcnt lgkmcnt(0)
	s_barrier
	ds_read2st64_b32 v[94:95], v0 offset1:1
	ds_read2st64_b32 v[96:97], v0 offset0:2 offset1:3
	ds_read2st64_b32 v[98:99], v0 offset0:4 offset1:5
	ds_read2st64_b32 v[100:101], v0 offset0:6 offset1:7
	global_load_dwordx4 v[252:255], v[84:85], off offset:16
	global_load_dwordx4 v[248:251], v[84:85], off
	s_waitcnt vmcnt(5)
	v_lshlrev_b32_e32 v104, 16, v72
	v_and_b32_e32 v105, 0xffff0000, v72
	v_mul_f32_e32 v0, 0xbfb8aa3b, v104
	v_lshlrev_b64 v[102:103], 11, v[2:3]
	v_exp_f32_e32 v0, v0
	v_mul_f32_e32 v2, 0xbfb8aa3b, v105
	v_exp_f32_e32 v2, v2
	v_lshlrev_b32_e32 v106, 16, v73
	v_add_f32_e32 v0, 1.0, v0
	v_rcp_f32_e32 v72, v0
	v_add_f32_e32 v0, 1.0, v2
	v_mul_f32_e32 v2, 0xbfb8aa3b, v106
	v_exp_f32_e32 v2, v2
	v_and_b32_e32 v107, 0xffff0000, v73
	v_mul_f32_e32 v73, 0xbfb8aa3b, v107
	v_lshlrev_b32_e32 v110, 16, v74
	v_exp_f32_e32 v109, v73
	v_rcp_f32_e32 v73, v0
	v_add_f32_e32 v0, 1.0, v2
	v_and_b32_e32 v111, 0xffff0000, v74
	v_mul_f32_e32 v2, 0xbfb8aa3b, v110
	v_exp_f32_e32 v2, v2
	v_mul_f32_e32 v74, 0xbfb8aa3b, v111
	v_exp_f32_e32 v112, v74
	v_rcp_f32_e32 v108, v0
	v_add_f32_e32 v0, 1.0, v109
	v_rcp_f32_e32 v109, v0
	v_add_f32_e32 v0, 1.0, v2
	v_rcp_f32_e32 v74, v0
	v_add_f32_e32 v0, 1.0, v112
	v_lshlrev_b32_e32 v112, 16, v75
	v_and_b32_e32 v113, 0xffff0000, v75
	v_mul_f32_e32 v2, 0xbfb8aa3b, v112
	v_exp_f32_e32 v2, v2
	v_mul_f32_e32 v75, 0xbfb8aa3b, v113
	v_exp_f32_e32 v115, v75
	v_rcp_f32_e32 v75, v0
	v_add_f32_e32 v0, 1.0, v2
	v_rcp_f32_e32 v114, v0
	v_add_f32_e32 v0, 1.0, v115
	v_rcp_f32_e32 v115, v0
	v_lshl_add_u32 v0, v129, 2, s96
	v_pk_mul_f32 v[106:107], v[108:109], v[106:107]
	v_pk_mul_f32 v[108:109], v[74:75], v[110:111]
	ds_read2st64_b32 v[74:75], v0 offset1:1
	v_pk_mul_f32 v[110:111], v[114:115], v[112:113]
	ds_read2st64_b32 v[112:113], v0 offset0:2 offset1:3
	ds_read2st64_b32 v[114:115], v0 offset0:4 offset1:5
	ds_read2st64_b32 v[116:117], v0 offset0:6 offset1:7
	s_waitcnt lgkmcnt(7)
	v_mov_b32_e32 v119, v94
	v_ashrrev_i32_e32 v133, 31, v132
	s_waitcnt lgkmcnt(3)
	v_mov_b32_e32 v118, v74
	v_pk_add_f32 v[118:119], v[118:119], 0 op_sel_hi:[1,0]
	v_mov_b32_e32 v94, v75
	v_pk_add_f32 v[74:75], v[118:119], v[94:95]
	s_waitcnt lgkmcnt(2)
	v_mov_b32_e32 v94, v112
	v_mov_b32_e32 v95, v96
	v_pk_add_f32 v[74:75], v[74:75], v[94:95]
	v_mov_b32_e32 v96, v113
	v_pk_add_f32 v[74:75], v[74:75], v[96:97]
	s_waitcnt lgkmcnt(1)
	v_mov_b32_e32 v94, v114
	v_mov_b32_e32 v95, v98
	v_pk_add_f32 v[74:75], v[74:75], v[94:95]
	v_mov_b32_e32 v98, v115
	v_pk_add_f32 v[74:75], v[74:75], v[98:99]
	s_waitcnt lgkmcnt(0)
	v_mov_b32_e32 v94, v116
	v_mov_b32_e32 v95, v100
	v_pk_add_f32 v[74:75], v[74:75], v[94:95]
	v_mov_b32_e32 v100, v117
	v_pk_add_f32 v[94:95], v[74:75], v[100:101]
	v_mov_b64_e32 v[74:75], s[60:61]
	v_pk_fma_f32 v[94:95], v[94:95], s[58:59], v[74:75] op_sel_hi:[1,0,0]
	v_lshl_add_u64 v[102:103], s[28:29], 0, v[102:103]
	v_mul_f32_e32 v0, 0x4b800000, v95
	v_cmp_gt_f32_e32 vcc, s59, v95
	s_lshl_b32 s38, s2, 1
	v_pk_mul_f32 v[104:105], v[72:73], v[104:105]
	v_cndmask_b32_e32 v0, v95, v0, vcc
	v_rsq_f32_e32 v0, v0
	v_lshl_add_u64 v[102:103], v[102:103], 0, s[38:39]
	v_lshlrev_b64 v[72:73], 1, v[132:133]
	v_lshl_add_u64 v[96:97], v[102:103], 0, v[72:73]
	v_mul_f32_e32 v2, 0x45800000, v0
	v_cndmask_b32_e32 v0, v0, v2, vcc
	v_pk_mul_f32 v[80:81], v[80:81], v[0:1] op_sel_hi:[1,0]
	v_pk_mul_f32 v[82:83], v[82:83], v[0:1] op_sel_hi:[1,0]
	v_pk_mul_f32 v[76:77], v[76:77], v[0:1] op_sel_hi:[1,0]
	v_pk_mul_f32 v[78:79], v[78:79], v[0:1] op_sel_hi:[1,0]
	s_waitcnt vmcnt(0)
	v_pk_mul_f32 v[80:81], v[248:249], v[80:81]
	v_pk_mul_f32 v[82:83], v[250:251], v[82:83]
	v_pk_mul_f32 v[76:77], v[252:253], v[76:77]
	v_pk_mul_f32 v[78:79], v[254:255], v[78:79]
	v_mov_b32_e32 v127, v1
	v_pk_mul_f32 v[80:81], v[104:105], v[80:81]
	v_pk_mul_f32 v[82:83], v[106:107], v[82:83]
	v_pk_mul_f32 v[76:77], v[108:109], v[76:77]
	v_pk_mul_f32 v[78:79], v[110:111], v[78:79]
	v_lshl_add_u64 v[96:97], v[96:97], 0, v[126:127]
	v_cvt_pk_bf16_f32 v80, v80, v81
	v_cvt_pk_bf16_f32 v81, v82, v83
	v_cvt_pk_bf16_f32 v82, v76, v77
	v_cvt_pk_bf16_f32 v83, v78, v79
	global_store_dwordx4 v[96:97], v[80:83], off
	s_nop 1
	s_nop 0
	s_nop 0
	s_nop 0
	v_lshlrev_b32_e32 v86, 16, v68
	v_and_b32_e32 v87, 0xffff0000, v68
	v_lshlrev_b32_e32 v68, 16, v69
	v_and_b32_e32 v69, 0xffff0000, v69
	v_mul_f32_e32 v0, 0xbfb8aa3b, v86
	v_mul_f32_e32 v92, 0xbfb8aa3b, v69
	v_exp_f32_e32 v0, v0
	v_exp_f32_e32 v92, v92
	v_lshlrev_b32_e32 v88, 16, v70
	v_and_b32_e32 v89, 0xffff0000, v70
	v_mul_f32_e32 v2, 0xbfb8aa3b, v87
	v_mul_f32_e32 v70, 0xbfb8aa3b, v68
	v_add_f32_e32 v0, 1.0, v0
	v_mul_f32_e32 v93, 0xbfb8aa3b, v88
	v_exp_f32_e32 v2, v2
	v_exp_f32_e32 v70, v70
	v_add_f32_e32 v97, 1.0, v92
	v_rcp_f32_e32 v92, v0
	v_mul_f32_e32 v0, 0x4b800000, v94
	v_cmp_gt_f32_e32 vcc, s59, v94
	v_exp_f32_e32 v93, v93
	v_add_f32_e32 v2, 1.0, v2
	v_cndmask_b32_e32 v0, v94, v0, vcc
	v_rsq_f32_e32 v0, v0
	v_add_f32_e32 v70, 1.0, v70
	v_add_f32_e32 v98, 1.0, v93
	v_rcp_f32_e32 v93, v2
	v_rcp_f32_e32 v96, v70
	v_rcp_f32_e32 v97, v97
	v_mul_f32_e32 v2, 0x45800000, v0
	v_cndmask_b32_e32 v0, v0, v2, vcc
	v_pk_mul_f32 v[64:65], v[64:65], v[0:1] op_sel_hi:[1,0]
	v_pk_mul_f32 v[66:67], v[66:67], v[0:1] op_sel_hi:[1,0]
	v_pk_mul_f32 v[86:87], v[92:93], v[86:87]
	v_pk_mul_f32 v[68:69], v[96:97], v[68:69]
	v_pk_mul_f32 v[60:61], v[60:61], v[0:1] op_sel_hi:[1,0]
	v_mul_f32_e32 v95, 0xbfb8aa3b, v89
	v_exp_f32_e32 v95, v95
	v_rcp_f32_e32 v94, v98
	v_mov_b32_e32 v131, v3
	v_pk_mul_f32 v[62:63], v[62:63], v[0:1] op_sel_hi:[1,0]
	v_add_f32_e32 v95, 1.0, v95
	v_rcp_f32_e32 v95, v95
	v_lshlrev_b64 v[90:91], 11, v[130:131]
	v_lshl_add_u64 v[90:91], s[28:29], 0, v[90:91]
	v_lshl_add_u32 v0, v177, 2, s96
	v_mov_b32_e32 v129, v3
	s_add_i32 s80, s80, s75
	s_add_i32 s79, s79, s76
	s_cmpk_gt_i32 s82, 0x3ff
	s_cselect_b64 s[12:13], -1, 0
	s_nop 0
	v_pk_mul_f32 v[64:65], v[248:249], v[64:65]
	v_pk_mul_f32 v[66:67], v[250:251], v[66:67]
	s_nop 0
	v_pk_mul_f32 v[76:77], v[252:253], v[60:61]
	v_pk_mul_f32 v[60:61], v[86:87], v[64:65]
	v_pk_mul_f32 v[64:65], v[68:69], v[66:67]
	v_cvt_pk_bf16_f32 v60, v60, v61
	v_cvt_pk_bf16_f32 v61, v64, v65
	v_lshlrev_b32_e32 v64, 16, v71
	v_and_b32_e32 v65, 0xffff0000, v71
	v_mul_f32_e32 v2, 0xbfb8aa3b, v64
	v_exp_f32_e32 v2, v2
	v_mul_f32_e32 v66, 0xbfb8aa3b, v65
	v_exp_f32_e32 v69, v66
	v_pk_mul_f32 v[62:63], v[254:255], v[62:63]
	v_add_f32_e32 v2, 1.0, v2
	v_rcp_f32_e32 v68, v2
	v_add_f32_e32 v2, 1.0, v69
	v_rcp_f32_e32 v69, v2
	v_pk_mul_f32 v[66:67], v[94:95], v[88:89]
	v_lshlrev_b32_e32 v82, 16, v56
	v_pk_mul_f32 v[66:67], v[66:67], v[76:77]
	v_pk_mul_f32 v[64:65], v[68:69], v[64:65]
	v_and_b32_e32 v83, 0xffff0000, v56
	v_pk_mul_f32 v[64:65], v[64:65], v[62:63]
	v_cvt_pk_bf16_f32 v62, v66, v67
	v_cvt_pk_bf16_f32 v63, v64, v65
	v_lshl_add_u64 v[64:65], v[90:91], 0, s[38:39]
	v_lshl_add_u64 v[64:65], v[64:65], 0, v[72:73]
	v_lshl_add_u64 v[64:65], v[64:65], 0, v[126:127]
	global_store_dwordx4 v[64:65], v[60:63], off
	s_nop 1
	ds_read2st64_b32 v[68:69], v0 offset1:1
	ds_read2st64_b32 v[70:71], v0 offset0:2 offset1:3
	ds_read2st64_b32 v[76:77], v0 offset0:4 offset1:5
	ds_read2st64_b32 v[78:79], v0 offset0:6 offset1:7
	s_nop 0
	s_nop 0
	v_mul_f32_e32 v0, 0xbfb8aa3b, v82
	v_exp_f32_e32 v0, v0
	v_mul_f32_e32 v2, 0xbfb8aa3b, v83
	v_exp_f32_e32 v2, v2
	v_lshlrev_b32_e32 v56, 16, v57
	v_add_f32_e32 v0, 1.0, v0
	v_rcp_f32_e32 v86, v0
	v_add_f32_e32 v0, 1.0, v2
	v_rcp_f32_e32 v87, v0
	v_and_b32_e32 v57, 0xffff0000, v57
	v_mul_f32_e32 v0, 0xbfb8aa3b, v56
	v_exp_f32_e32 v0, v0
	v_mul_f32_e32 v2, 0xbfb8aa3b, v57
	v_exp_f32_e32 v2, v2
	v_pk_mul_f32 v[82:83], v[86:87], v[82:83]
	v_add_f32_e32 v0, 1.0, v0
	v_rcp_f32_e32 v86, v0
	v_add_f32_e32 v0, 1.0, v2
	v_lshlrev_b32_e32 v88, 16, v58
	v_rcp_f32_e32 v87, v0
	v_and_b32_e32 v89, 0xffff0000, v58
	v_mul_f32_e32 v0, 0xbfb8aa3b, v88
	v_exp_f32_e32 v0, v0
	v_mul_f32_e32 v2, 0xbfb8aa3b, v89
	v_exp_f32_e32 v2, v2
	v_pk_mul_f32 v[56:57], v[86:87], v[56:57]
	v_add_f32_e32 v0, 1.0, v0
	v_lshlrev_b32_e32 v86, 16, v59
	v_rcp_f32_e32 v58, v0
	v_add_f32_e32 v0, 1.0, v2
	v_and_b32_e32 v87, 0xffff0000, v59
	v_mul_f32_e32 v2, 0xbfb8aa3b, v86
	v_exp_f32_e32 v2, v2
	v_mul_f32_e32 v59, 0xbfb8aa3b, v87
	v_exp_f32_e32 v91, v59
	v_rcp_f32_e32 v59, v0
	v_add_f32_e32 v0, 1.0, v2
	v_rcp_f32_e32 v90, v0
	v_add_f32_e32 v0, 1.0, v91
	v_rcp_f32_e32 v91, v0
	v_lshl_add_u32 v0, v125, 2, s96
	v_pk_mul_f32 v[58:59], v[58:59], v[88:89]
	ds_read2st64_b32 v[88:89], v0 offset1:1
	v_pk_mul_f32 v[86:87], v[90:91], v[86:87]
	ds_read2st64_b32 v[90:91], v0 offset0:2 offset1:3
	ds_read2st64_b32 v[92:93], v0 offset0:4 offset1:5
	ds_read2st64_b32 v[94:95], v0 offset0:6 offset1:7
	s_waitcnt lgkmcnt(7)
	v_mov_b32_e32 v97, v68
	v_lshlrev_b64 v[80:81], 11, v[128:129]
	s_waitcnt lgkmcnt(3)
	v_mov_b32_e32 v96, v88
	v_pk_add_f32 v[96:97], v[96:97], 0 op_sel_hi:[1,0]
	v_mov_b32_e32 v68, v89
	v_pk_add_f32 v[68:69], v[96:97], v[68:69]
	s_waitcnt lgkmcnt(2)
	v_mov_b32_e32 v88, v90
	v_mov_b32_e32 v89, v70
	v_pk_add_f32 v[68:69], v[68:69], v[88:89]
	v_mov_b32_e32 v70, v91
	v_pk_add_f32 v[68:69], v[68:69], v[70:71]
	s_waitcnt lgkmcnt(1)
	v_mov_b32_e32 v70, v92
	v_mov_b32_e32 v71, v76
	v_pk_add_f32 v[68:69], v[68:69], v[70:71]
	v_mov_b32_e32 v76, v93
	v_pk_add_f32 v[68:69], v[68:69], v[76:77]
	s_waitcnt lgkmcnt(0)
	v_mov_b32_e32 v70, v94
	v_mov_b32_e32 v71, v78
	v_pk_add_f32 v[68:69], v[68:69], v[70:71]
	v_mov_b32_e32 v78, v95
	v_pk_add_f32 v[68:69], v[68:69], v[78:79]
	v_lshl_add_u64 v[80:81], s[28:29], 0, v[80:81]
	v_pk_fma_f32 v[68:69], v[68:69], s[58:59], v[74:75] op_sel_hi:[1,0,0]
	v_lshl_add_u64 v[70:71], v[80:81], 0, s[38:39]
	v_mul_f32_e32 v0, 0x4b800000, v69
	v_cmp_gt_f32_e32 vcc, s59, v69
	v_lshl_add_u64 v[70:71], v[70:71], 0, v[72:73]
	v_lshl_add_u64 v[70:71], v[70:71], 0, v[126:127]
	v_cndmask_b32_e32 v0, v69, v0, vcc
	v_rsq_f32_e32 v0, v0
	v_mov_b32_e32 v125, v3
	v_and_b32_e32 v3, 0xffff0000, v44
	v_mul_f32_e32 v2, 0x45800000, v0
	v_cndmask_b32_e32 v0, v0, v2, vcc
	v_pk_mul_f32 v[52:53], v[52:53], v[0:1] op_sel_hi:[1,0]
	v_pk_mul_f32 v[54:55], v[54:55], v[0:1] op_sel_hi:[1,0]
	v_pk_mul_f32 v[48:49], v[48:49], v[0:1] op_sel_hi:[1,0]
	v_pk_mul_f32 v[50:51], v[50:51], v[0:1] op_sel_hi:[1,0]
	s_nop 0
	v_pk_mul_f32 v[52:53], v[248:249], v[52:53]
	v_pk_mul_f32 v[54:55], v[250:251], v[54:55]
	v_pk_mul_f32 v[48:49], v[252:253], v[48:49]
	v_pk_mul_f32 v[50:51], v[254:255], v[50:51]
	v_pk_mul_f32 v[52:53], v[82:83], v[52:53]
	v_pk_mul_f32 v[54:55], v[56:57], v[54:55]
	v_pk_mul_f32 v[48:49], v[58:59], v[48:49]
	v_pk_mul_f32 v[50:51], v[86:87], v[50:51]
	v_cvt_pk_bf16_f32 v52, v52, v53
	v_cvt_pk_bf16_f32 v53, v54, v55
	v_cvt_pk_bf16_f32 v54, v48, v49
	v_cvt_pk_bf16_f32 v55, v50, v51
	global_store_dwordx4 v[70:71], v[52:55], off
	s_nop 1
	s_nop 0
	s_nop 0
	s_nop 0
	v_lshlrev_b32_e32 v2, 16, v44
	v_mul_f32_e32 v0, 0xbfb8aa3b, v2
	v_mul_f32_e32 v58, 0xbfb8aa3b, v3
	v_exp_f32_e32 v0, v0
	v_lshlrev_b32_e32 v44, 16, v45
	v_exp_f32_e32 v58, v58
	v_mul_f32_e32 v59, 0xbfb8aa3b, v44
	v_and_b32_e32 v45, 0xffff0000, v45
	v_exp_f32_e32 v59, v59
	v_mul_f32_e32 v60, 0xbfb8aa3b, v45
	v_add_f32_e32 v0, 1.0, v0
	v_exp_f32_e32 v60, v60
	v_add_f32_e32 v61, 1.0, v58
	v_rcp_f32_e32 v58, v0
	v_mul_f32_e32 v0, 0x4b800000, v68
	v_cmp_gt_f32_e32 vcc, s59, v68
	v_add_f32_e32 v62, 1.0, v59
	v_rcp_f32_e32 v59, v61
	v_cndmask_b32_e32 v0, v68, v0, vcc
	v_rsq_f32_e32 v0, v0
	v_add_f32_e32 v63, 1.0, v60
	v_rcp_f32_e32 v60, v62
	v_rcp_f32_e32 v61, v63
	v_pk_mul_f32 v[2:3], v[58:59], v[2:3]
	v_mul_f32_e32 v58, 0x45800000, v0
	v_cndmask_b32_e32 v0, v0, v58, vcc
	v_pk_mul_f32 v[42:43], v[42:43], v[0:1] op_sel_hi:[1,0]
	v_pk_mul_f32 v[44:45], v[60:61], v[44:45]
	v_pk_mul_f32 v[40:41], v[40:41], v[0:1] op_sel_hi:[1,0]
	v_pk_mul_f32 v[36:37], v[36:37], v[0:1] op_sel_hi:[1,0]
	v_lshlrev_b64 v[56:57], 11, v[124:125]
	v_lshl_add_u64 v[56:57], s[28:29], 0, v[56:57]
	s_nop 0
	v_pk_mul_f32 v[42:43], v[250:251], v[42:43]
	v_pk_mul_f32 v[40:41], v[248:249], v[40:41]
	v_pk_mul_f32 v[42:43], v[44:45], v[42:43]
	v_lshlrev_b32_e32 v44, 16, v46
	v_pk_mul_f32 v[2:3], v[2:3], v[40:41]
	v_mul_f32_e32 v40, 0xbfb8aa3b, v44
	v_and_b32_e32 v45, 0xffff0000, v46
	v_exp_f32_e32 v48, v40
	v_cvt_pk_bf16_f32 v40, v2, v3
	v_mul_f32_e32 v3, 0xbfb8aa3b, v45
	v_exp_f32_e32 v3, v3
	v_cvt_pk_bf16_f32 v41, v42, v43
	v_lshlrev_b32_e32 v42, 16, v47
	v_and_b32_e32 v43, 0xffff0000, v47
	v_add_f32_e32 v2, 1.0, v48
	v_add_f32_e32 v3, 1.0, v3
	v_mul_f32_e32 v46, 0xbfb8aa3b, v42
	v_mul_f32_e32 v47, 0xbfb8aa3b, v43
	v_rcp_f32_e32 v2, v2
	v_rcp_f32_e32 v3, v3
	v_exp_f32_e32 v46, v46
	v_exp_f32_e32 v47, v47
	s_nop 0
	v_pk_mul_f32 v[36:37], v[252:253], v[36:37]
	v_pk_mul_f32 v[2:3], v[2:3], v[44:45]
	v_add_f32_e32 v44, 1.0, v46
	v_add_f32_e32 v45, 1.0, v47
	v_rcp_f32_e32 v44, v44
	v_rcp_f32_e32 v45, v45
	v_pk_mul_f32 v[2:3], v[2:3], v[36:37]
	v_pk_mul_f32 v[36:37], v[38:39], v[0:1] op_sel_hi:[1,0]
	v_pk_mul_f32 v[38:39], v[44:45], v[42:43]
	v_pk_mul_f32 v[36:37], v[254:255], v[36:37]
	v_cvt_pk_bf16_f32 v42, v2, v3
	v_lshl_add_u64 v[2:3], v[56:57], 0, s[38:39]
	v_pk_mul_f32 v[36:37], v[38:39], v[36:37]
	v_lshl_add_u64 v[2:3], v[2:3], 0, v[72:73]
	v_cvt_pk_bf16_f32 v43, v36, v37
	v_lshl_add_u64 v[2:3], v[2:3], 0, v[126:127]
	global_store_dwordx4 v[2:3], v[40:43], off
	s_nop 1
	s_nop 0

.LBB0_1634:
	s_or_b64 exec, exec, s[12:13]
	s_lshl_b32 s12, s2, 2
	s_add_u32 s12, s26, s12
	s_addc_u32 s13, s27, 0
	v_lshl_add_u32 v0, v131, 2, s96
	v_lshl_add_u64 v[84:85], v[84:85], 2, s[12:13]
	s_waitcnt lgkmcnt(0)
	s_barrier
	ds_read2st64_b32 v[94:95], v0 offset1:1
	ds_read2st64_b32 v[96:97], v0 offset0:2 offset1:3
	ds_read2st64_b32 v[98:99], v0 offset0:4 offset1:5
	ds_read2st64_b32 v[100:101], v0 offset0:6 offset1:7
	global_load_dwordx4 v[252:255], v[84:85], off offset:16
	global_load_dwordx4 v[248:251], v[84:85], off
	s_waitcnt vmcnt(5)
	v_lshlrev_b32_e32 v104, 16, v72
	v_and_b32_e32 v105, 0xffff0000, v72
	v_mul_f32_e32 v0, 0xbfb8aa3b, v104
	v_exp_f32_e32 v0, v0
	v_mul_f32_e32 v72, 0xbfb8aa3b, v105
	v_exp_f32_e32 v106, v72
	v_and_b32_e32 v107, 0xffff0000, v73
	v_add_f32_e32 v0, 1.0, v0
	v_rcp_f32_e32 v72, v0
	v_add_f32_e32 v0, 1.0, v106
	v_lshlrev_b32_e32 v106, 16, v73
	v_mul_f32_e32 v73, 0xbfb8aa3b, v106
	v_exp_f32_e32 v108, v73
	v_mul_f32_e32 v73, 0xbfb8aa3b, v107
	v_exp_f32_e32 v109, v73
	v_lshlrev_b32_e32 v110, 16, v74
	v_rcp_f32_e32 v73, v0
	v_add_f32_e32 v0, 1.0, v108
	v_and_b32_e32 v111, 0xffff0000, v74
	v_mul_f32_e32 v74, 0xbfb8aa3b, v110
	v_rcp_f32_e32 v108, v0
	v_add_f32_e32 v0, 1.0, v109
	v_exp_f32_e32 v74, v74
	v_mul_f32_e32 v109, 0xbfb8aa3b, v111
	v_exp_f32_e32 v112, v109
	v_rcp_f32_e32 v109, v0
	v_add_f32_e32 v0, 1.0, v74
	v_rcp_f32_e32 v74, v0
	v_add_f32_e32 v0, 1.0, v112
	v_lshlrev_b32_e32 v112, 16, v75
	v_and_b32_e32 v113, 0xffff0000, v75
	v_mul_f32_e32 v75, 0xbfb8aa3b, v112
	v_exp_f32_e32 v114, v75
	v_mul_f32_e32 v75, 0xbfb8aa3b, v113
	v_exp_f32_e32 v115, v75
	v_rcp_f32_e32 v75, v0
	v_add_f32_e32 v0, 1.0, v114
	v_rcp_f32_e32 v114, v0
	v_add_f32_e32 v0, 1.0, v115
	v_rcp_f32_e32 v115, v0
	v_lshl_add_u32 v0, v129, 2, s96
	v_pk_mul_f32 v[106:107], v[108:109], v[106:107]
	v_pk_mul_f32 v[108:109], v[74:75], v[110:111]
	ds_read2st64_b32 v[74:75], v0 offset1:1
	v_pk_mul_f32 v[110:111], v[114:115], v[112:113]
	ds_read2st64_b32 v[112:113], v0 offset0:2 offset1:3
	ds_read2st64_b32 v[114:115], v0 offset0:4 offset1:5
	ds_read2st64_b32 v[116:117], v0 offset0:6 offset1:7
	s_waitcnt lgkmcnt(7)
	v_mov_b32_e32 v119, v94
	v_lshlrev_b64 v[102:103], 11, v[124:125]
	s_waitcnt lgkmcnt(3)
	v_mov_b32_e32 v118, v74
	v_pk_add_f32 v[118:119], v[118:119], 0 op_sel_hi:[1,0]
	v_mov_b32_e32 v94, v75
	v_pk_add_f32 v[74:75], v[118:119], v[94:95]
	s_waitcnt lgkmcnt(2)
	v_mov_b32_e32 v94, v112
	v_mov_b32_e32 v95, v96
	v_pk_add_f32 v[74:75], v[74:75], v[94:95]
	v_mov_b32_e32 v96, v113
	v_pk_add_f32 v[74:75], v[74:75], v[96:97]
	s_waitcnt lgkmcnt(1)
	v_mov_b32_e32 v94, v114
	v_mov_b32_e32 v95, v98
	v_pk_add_f32 v[74:75], v[74:75], v[94:95]
	v_mov_b32_e32 v98, v115
	v_pk_add_f32 v[74:75], v[74:75], v[98:99]
	s_waitcnt lgkmcnt(0)
	v_mov_b32_e32 v94, v116
	v_mov_b32_e32 v95, v100
	v_pk_add_f32 v[74:75], v[74:75], v[94:95]
	v_mov_b32_e32 v100, v117
	v_pk_add_f32 v[94:95], v[74:75], v[100:101]
	v_mov_b64_e32 v[74:75], s[60:61]
	v_pk_fma_f32 v[94:95], v[94:95], s[58:59], v[74:75] op_sel_hi:[1,0,0]
	v_ashrrev_i32_e32 v133, 31, v132
	v_mul_f32_e32 v0, 0x4b800000, v95
	v_cmp_gt_f32_e32 vcc, s59, v95
	v_lshl_add_u64 v[102:103], s[28:29], 0, v[102:103]
	s_lshl_b32 s38, s2, 1
	v_cndmask_b32_e32 v0, v95, v0, vcc
	v_rsq_f32_e32 v0, v0
	v_pk_mul_f32 v[104:105], v[72:73], v[104:105]
	v_lshl_add_u64 v[102:103], v[102:103], 0, s[38:39]
	v_lshlrev_b64 v[72:73], 1, v[132:133]
	v_mul_f32_e32 v95, 0x45800000, v0
	v_cndmask_b32_e32 v0, v0, v95, vcc
	v_pk_mul_f32 v[80:81], v[80:81], v[0:1] op_sel_hi:[1,0]
	v_pk_mul_f32 v[82:83], v[82:83], v[0:1] op_sel_hi:[1,0]
	v_pk_mul_f32 v[76:77], v[76:77], v[0:1] op_sel_hi:[1,0]
	v_pk_mul_f32 v[78:79], v[78:79], v[0:1] op_sel_hi:[1,0]
	s_waitcnt vmcnt(0)
	v_pk_mul_f32 v[80:81], v[248:249], v[80:81]
	v_pk_mul_f32 v[82:83], v[250:251], v[82:83]
	v_pk_mul_f32 v[76:77], v[252:253], v[76:77]
	v_pk_mul_f32 v[78:79], v[254:255], v[78:79]
	v_lshl_add_u64 v[96:97], v[102:103], 0, v[72:73]
	v_mov_b32_e32 v127, v1
	v_pk_mul_f32 v[80:81], v[104:105], v[80:81]
	v_pk_mul_f32 v[82:83], v[106:107], v[82:83]
	v_pk_mul_f32 v[76:77], v[108:109], v[76:77]
	v_pk_mul_f32 v[78:79], v[110:111], v[78:79]
	v_lshl_add_u64 v[96:97], v[96:97], 0, v[126:127]
	v_cvt_pk_bf16_f32 v80, v80, v81
	v_cvt_pk_bf16_f32 v81, v82, v83
	v_cvt_pk_bf16_f32 v82, v76, v77
	v_cvt_pk_bf16_f32 v83, v78, v79
	global_store_dwordx4 v[96:97], v[80:83], off
	s_nop 1
	s_nop 0
	s_nop 0
	s_nop 0
	v_lshlrev_b32_e32 v86, 16, v68
	v_and_b32_e32 v87, 0xffff0000, v68
	v_lshlrev_b32_e32 v68, 16, v69
	v_mul_f32_e32 v0, 0xbfb8aa3b, v86
	v_mul_f32_e32 v92, 0xbfb8aa3b, v68
	v_exp_f32_e32 v0, v0
	v_exp_f32_e32 v92, v92
	v_and_b32_e32 v69, 0xffff0000, v69
	v_lshlrev_b32_e32 v88, 16, v70
	v_and_b32_e32 v89, 0xffff0000, v70
	v_mul_f32_e32 v70, 0xbfb8aa3b, v87
	v_mul_f32_e32 v93, 0xbfb8aa3b, v69
	v_add_f32_e32 v0, 1.0, v0
	v_mul_f32_e32 v96, 0xbfb8aa3b, v89
	v_exp_f32_e32 v70, v70
	v_exp_f32_e32 v93, v93
	v_add_f32_e32 v97, 1.0, v92
	v_rcp_f32_e32 v92, v0
	v_mul_f32_e32 v0, 0x4b800000, v94
	v_cmp_gt_f32_e32 vcc, s59, v94
	v_exp_f32_e32 v96, v96
	v_add_f32_e32 v70, 1.0, v70
	v_cndmask_b32_e32 v0, v94, v0, vcc
	v_rsq_f32_e32 v0, v0
	v_add_f32_e32 v98, 1.0, v93
	v_add_f32_e32 v99, 1.0, v96
	v_rcp_f32_e32 v93, v70
	v_rcp_f32_e32 v96, v97
	v_rcp_f32_e32 v97, v98
	v_mul_f32_e32 v70, 0x45800000, v0
	v_cndmask_b32_e32 v0, v0, v70, vcc
	v_pk_mul_f32 v[64:65], v[64:65], v[0:1] op_sel_hi:[1,0]
	v_pk_mul_f32 v[66:67], v[66:67], v[0:1] op_sel_hi:[1,0]
	v_pk_mul_f32 v[86:87], v[92:93], v[86:87]
	v_pk_mul_f32 v[68:69], v[96:97], v[68:69]
	v_pk_mul_f32 v[60:61], v[60:61], v[0:1] op_sel_hi:[1,0]
	v_mul_f32_e32 v95, 0xbfb8aa3b, v88
	v_exp_f32_e32 v95, v95
	v_rcp_f32_e32 v99, v99
	v_mov_b32_e32 v131, v125
	v_pk_mul_f32 v[62:63], v[62:63], v[0:1] op_sel_hi:[1,0]
	v_add_f32_e32 v95, 1.0, v95
	v_rcp_f32_e32 v98, v95
	v_lshlrev_b64 v[90:91], 11, v[130:131]
	v_lshl_add_u64 v[90:91], s[28:29], 0, v[90:91]
	v_lshl_add_u32 v0, v177, 2, s96
	v_mov_b32_e32 v129, v125
	s_cmpk_gt_i32 s81, 0x3ff
	s_mov_b64 s[12:13], -1
	s_nop 0
	v_pk_mul_f32 v[64:65], v[248:249], v[64:65]
	v_pk_mul_f32 v[66:67], v[250:251], v[66:67]
	s_nop 0
	v_pk_mul_f32 v[76:77], v[252:253], v[60:61]
	v_pk_mul_f32 v[60:61], v[86:87], v[64:65]
	v_pk_mul_f32 v[64:65], v[68:69], v[66:67]
	v_cvt_pk_bf16_f32 v60, v60, v61
	v_cvt_pk_bf16_f32 v61, v64, v65
	v_lshlrev_b32_e32 v64, 16, v71
	v_and_b32_e32 v65, 0xffff0000, v71
	v_mul_f32_e32 v66, 0xbfb8aa3b, v64
	v_exp_f32_e32 v68, v66
	v_mul_f32_e32 v66, 0xbfb8aa3b, v65
	v_exp_f32_e32 v69, v66
	v_pk_mul_f32 v[62:63], v[254:255], v[62:63]
	v_add_f32_e32 v68, 1.0, v68
	v_rcp_f32_e32 v68, v68
	v_add_f32_e32 v69, 1.0, v69
	v_rcp_f32_e32 v69, v69
	v_pk_mul_f32 v[66:67], v[98:99], v[88:89]
	v_lshlrev_b32_e32 v82, 16, v56
	v_pk_mul_f32 v[66:67], v[66:67], v[76:77]
	v_pk_mul_f32 v[64:65], v[68:69], v[64:65]
	v_and_b32_e32 v83, 0xffff0000, v56
	v_pk_mul_f32 v[64:65], v[64:65], v[62:63]
	v_cvt_pk_bf16_f32 v62, v66, v67
	v_cvt_pk_bf16_f32 v63, v64, v65
	v_lshl_add_u64 v[64:65], v[90:91], 0, s[38:39]
	v_lshl_add_u64 v[64:65], v[64:65], 0, v[72:73]
	v_lshl_add_u64 v[64:65], v[64:65], 0, v[126:127]
	global_store_dwordx4 v[64:65], v[60:63], off
	s_nop 1
	ds_read2st64_b32 v[68:69], v0 offset1:1
	ds_read2st64_b32 v[70:71], v0 offset0:2 offset1:3
	ds_read2st64_b32 v[76:77], v0 offset0:4 offset1:5
	ds_read2st64_b32 v[78:79], v0 offset0:6 offset1:7
	s_nop 0
	s_nop 0
	v_mul_f32_e32 v0, 0xbfb8aa3b, v82
	v_exp_f32_e32 v0, v0
	v_mul_f32_e32 v56, 0xbfb8aa3b, v83
	v_exp_f32_e32 v56, v56
	v_and_b32_e32 v89, 0xffff0000, v58
	v_add_f32_e32 v0, 1.0, v0
	v_rcp_f32_e32 v86, v0
	v_add_f32_e32 v0, 1.0, v56
	v_lshlrev_b32_e32 v56, 16, v57
	v_rcp_f32_e32 v87, v0
	v_and_b32_e32 v57, 0xffff0000, v57
	v_mul_f32_e32 v0, 0xbfb8aa3b, v56
	v_exp_f32_e32 v0, v0
	v_mul_f32_e32 v88, 0xbfb8aa3b, v57
	v_exp_f32_e32 v88, v88
	v_pk_mul_f32 v[82:83], v[86:87], v[82:83]
	v_add_f32_e32 v0, 1.0, v0
	v_rcp_f32_e32 v86, v0
	v_add_f32_e32 v0, 1.0, v88
	v_lshlrev_b32_e32 v88, 16, v58
	v_rcp_f32_e32 v87, v0
	v_mul_f32_e32 v0, 0xbfb8aa3b, v88
	v_exp_f32_e32 v0, v0
	v_mul_f32_e32 v58, 0xbfb8aa3b, v89
	v_exp_f32_e32 v90, v58
	v_pk_mul_f32 v[56:57], v[86:87], v[56:57]
	v_lshlrev_b32_e32 v86, 16, v59
	v_add_f32_e32 v0, 1.0, v0
	v_and_b32_e32 v87, 0xffff0000, v59
	v_mul_f32_e32 v59, 0xbfb8aa3b, v86
	v_rcp_f32_e32 v58, v0
	v_add_f32_e32 v0, 1.0, v90
	v_exp_f32_e32 v90, v59
	v_mul_f32_e32 v59, 0xbfb8aa3b, v87
	v_exp_f32_e32 v91, v59
	v_rcp_f32_e32 v59, v0
	v_add_f32_e32 v0, 1.0, v90
	v_rcp_f32_e32 v90, v0
	v_add_f32_e32 v0, 1.0, v91
	v_rcp_f32_e32 v91, v0
	v_lshl_add_u32 v0, v3, 2, s96
	v_pk_mul_f32 v[58:59], v[58:59], v[88:89]
	ds_read2st64_b32 v[88:89], v0 offset1:1
	v_pk_mul_f32 v[86:87], v[90:91], v[86:87]
	ds_read2st64_b32 v[90:91], v0 offset0:2 offset1:3
	ds_read2st64_b32 v[92:93], v0 offset0:4 offset1:5
	ds_read2st64_b32 v[94:95], v0 offset0:6 offset1:7
	s_waitcnt lgkmcnt(7)
	v_mov_b32_e32 v97, v68
	v_lshlrev_b64 v[80:81], 11, v[128:129]
	s_waitcnt lgkmcnt(3)
	v_mov_b32_e32 v96, v88
	v_pk_add_f32 v[96:97], v[96:97], 0 op_sel_hi:[1,0]
	v_mov_b32_e32 v68, v89
	v_pk_add_f32 v[68:69], v[96:97], v[68:69]
	s_waitcnt lgkmcnt(2)
	v_mov_b32_e32 v88, v90
	v_mov_b32_e32 v89, v70
	v_pk_add_f32 v[68:69], v[68:69], v[88:89]
	v_mov_b32_e32 v70, v91
	v_pk_add_f32 v[68:69], v[68:69], v[70:71]
	s_waitcnt lgkmcnt(1)
	v_mov_b32_e32 v70, v92
	v_mov_b32_e32 v71, v76
	v_pk_add_f32 v[68:69], v[68:69], v[70:71]
	v_mov_b32_e32 v76, v93
	v_pk_add_f32 v[68:69], v[68:69], v[76:77]
	s_waitcnt lgkmcnt(0)
	v_mov_b32_e32 v70, v94
	v_mov_b32_e32 v71, v78
	v_pk_add_f32 v[68:69], v[68:69], v[70:71]
	v_mov_b32_e32 v78, v95
	v_pk_add_f32 v[68:69], v[68:69], v[78:79]
	v_lshl_add_u64 v[80:81], s[28:29], 0, v[80:81]
	v_pk_fma_f32 v[68:69], v[68:69], s[58:59], v[74:75] op_sel_hi:[1,0,0]
	v_lshl_add_u64 v[70:71], v[80:81], 0, s[38:39]
	v_mul_f32_e32 v0, 0x4b800000, v69
	v_cmp_gt_f32_e32 vcc, s59, v69
	v_lshl_add_u64 v[70:71], v[70:71], 0, v[72:73]
	v_lshl_add_u64 v[70:71], v[70:71], 0, v[126:127]
	v_cndmask_b32_e32 v0, v69, v0, vcc
	v_rsq_f32_e32 v0, v0
	s_nop 0
	v_mul_f32_e32 v3, 0x45800000, v0
	v_cndmask_b32_e32 v0, v0, v3, vcc
	v_pk_mul_f32 v[52:53], v[52:53], v[0:1] op_sel_hi:[1,0]
	v_pk_mul_f32 v[54:55], v[54:55], v[0:1] op_sel_hi:[1,0]
	v_pk_mul_f32 v[48:49], v[48:49], v[0:1] op_sel_hi:[1,0]
	v_pk_mul_f32 v[50:51], v[50:51], v[0:1] op_sel_hi:[1,0]
	s_nop 0
	v_pk_mul_f32 v[52:53], v[248:249], v[52:53]
	v_pk_mul_f32 v[54:55], v[250:251], v[54:55]
	v_pk_mul_f32 v[48:49], v[252:253], v[48:49]
	v_pk_mul_f32 v[50:51], v[254:255], v[50:51]
	v_pk_mul_f32 v[52:53], v[82:83], v[52:53]
	v_pk_mul_f32 v[54:55], v[56:57], v[54:55]
	v_pk_mul_f32 v[48:49], v[58:59], v[48:49]
	v_pk_mul_f32 v[50:51], v[86:87], v[50:51]
	v_cvt_pk_bf16_f32 v52, v52, v53
	v_cvt_pk_bf16_f32 v53, v54, v55
	v_cvt_pk_bf16_f32 v54, v48, v49
	v_cvt_pk_bf16_f32 v55, v50, v51
	global_store_dwordx4 v[70:71], v[52:55], off
	s_nop 1
	s_nop 0
	s_nop 0
	s_nop 0
	v_lshlrev_b32_e32 v56, 16, v44
	v_and_b32_e32 v57, 0xffff0000, v44
	v_lshlrev_b32_e32 v44, 16, v45
	v_mul_f32_e32 v0, 0xbfb8aa3b, v56
	v_mul_f32_e32 v60, 0xbfb8aa3b, v44
	v_exp_f32_e32 v0, v0
	v_exp_f32_e32 v60, v60
	v_and_b32_e32 v45, 0xffff0000, v45
	v_mul_f32_e32 v61, 0xbfb8aa3b, v45
	v_add_f32_e32 v0, 1.0, v0
	v_mul_f32_e32 v59, 0xbfb8aa3b, v57
	v_exp_f32_e32 v61, v61
	v_add_f32_e32 v62, 1.0, v60
	v_rcp_f32_e32 v60, v0
	v_mul_f32_e32 v0, 0x4b800000, v68
	v_cmp_gt_f32_e32 vcc, s59, v68
	v_exp_f32_e32 v59, v59
	v_add_f32_e32 v63, 1.0, v61
	v_cndmask_b32_e32 v0, v68, v0, vcc
	v_rsq_f32_e32 v0, v0
	v_add_f32_e32 v59, 1.0, v59
	v_rcp_f32_e32 v62, v62
	v_rcp_f32_e32 v63, v63
	v_rcp_f32_e32 v61, v59
	v_mul_f32_e32 v59, 0x45800000, v0
	v_cndmask_b32_e32 v0, v0, v59, vcc
	v_pk_mul_f32 v[42:43], v[42:43], v[0:1] op_sel_hi:[1,0]
	v_lshlrev_b32_e32 v58, 16, v46
	v_pk_mul_f32 v[44:45], v[62:63], v[44:45]
	v_pk_mul_f32 v[40:41], v[40:41], v[0:1] op_sel_hi:[1,0]
	v_pk_mul_f32 v[56:57], v[60:61], v[56:57]
	v_and_b32_e32 v59, 0xffff0000, v46
	v_mov_b32_e32 v3, v125
	v_lshlrev_b64 v[2:3], 11, v[2:3]
	v_pk_mul_f32 v[36:37], v[36:37], v[0:1] op_sel_hi:[1,0]
	v_lshl_add_u64 v[2:3], s[28:29], 0, v[2:3]
	v_pk_mul_f32 v[38:39], v[38:39], v[0:1] op_sel_hi:[1,0]
	v_lshl_add_u64 v[2:3], v[2:3], 0, s[38:39]
	v_lshl_add_u64 v[2:3], v[2:3], 0, v[72:73]
	v_lshl_add_u64 v[2:3], v[2:3], 0, v[126:127]
	s_nop 0
	v_pk_mul_f32 v[42:43], v[250:251], v[42:43]
	s_nop 0
	v_pk_mul_f32 v[42:43], v[44:45], v[42:43]
	v_mul_f32_e32 v44, 0xbfb8aa3b, v58
	v_exp_f32_e32 v44, v44
	v_pk_mul_f32 v[40:41], v[248:249], v[40:41]
	v_and_b32_e32 v45, 0xffff0000, v47
	v_pk_mul_f32 v[40:41], v[56:57], v[40:41]
	s_nop 0
	v_pk_mul_f32 v[36:37], v[252:253], v[36:37]
	v_cvt_pk_bf16_f32 v40, v40, v41
	v_cvt_pk_bf16_f32 v41, v42, v43
	v_add_f32_e32 v42, 1.0, v44
	v_mul_f32_e32 v43, 0xbfb8aa3b, v59
	v_lshlrev_b32_e32 v44, 16, v47
	v_exp_f32_e32 v43, v43
	v_mul_f32_e32 v46, 0xbfb8aa3b, v44
	v_mul_f32_e32 v47, 0xbfb8aa3b, v45
	v_exp_f32_e32 v46, v46
	v_exp_f32_e32 v47, v47
	v_add_f32_e32 v43, 1.0, v43
	v_rcp_f32_e32 v42, v42
	v_rcp_f32_e32 v43, v43
	v_add_f32_e32 v46, 1.0, v46
	v_add_f32_e32 v47, 1.0, v47
	v_rcp_f32_e32 v46, v46
	v_rcp_f32_e32 v47, v47
	v_pk_mul_f32 v[42:43], v[42:43], v[58:59]
	v_pk_mul_f32 v[38:39], v[254:255], v[38:39]
	v_pk_mul_f32 v[36:37], v[42:43], v[36:37]
	v_pk_mul_f32 v[42:43], v[46:47], v[44:45]
	s_nop 0
	v_pk_mul_f32 v[38:39], v[42:43], v[38:39]
	v_cvt_pk_bf16_f32 v42, v36, v37
	v_cvt_pk_bf16_f32 v43, v38, v39
	global_store_dwordx4 v[2:3], v[40:43], off
	s_nop 1
	s_nop 0
	s_cbranch_scc1 .LBB0_1595
	s_add_i32 s2, s74, s82
	s_cmpk_gt_i32 s2, 0x3ff
	s_cbranch_scc1 .LBB0_1637
	v_mov_b32_e32 v0, v204
	s_ashr_i32 s12, s2, 8
	v_ashrrev_i32_e32 v2, 31, v0
	v_lshrrev_b32_e32 v2, 27, v2
	v_add_u32_e32 v3, v0, v2
	s_ashr_i32 s13, s12, 31
	s_add_i32 s2, s75, s80
	v_ashrrev_i32_e32 v2, 5, v3
	v_and_b32_e32 v3, 0x1fffffe0, v3
	s_lshl_b64 s[12:13], s[12:13], 12
	s_and_b32 s2, s2, 0xfc0
	v_sub_u32_e32 v3, v0, v3
	s_or_b32 s12, s12, s2
	v_lshlrev_b32_e32 v4, 3, v3
	v_ashrrev_i32_e32 v3, 31, v2
	s_add_i32 s2, s76, s79
	v_lshl_add_u64 v[2:3], s[12:13], 0, v[2:3]
	v_mov_b64_e32 v[20:21], s[30:31]
	s_and_b32 s2, s2, 0x300
	v_mad_u64_u32 v[6:7], s[14:15], v2, s33, v[20:21]
	v_mad_i32_i24 v7, v3, s33, v7
	s_lshl_b32 s38, s2, 1
	v_lshl_add_u64 v[2:3], v[6:7], 0, s[38:39]
	v_ashrrev_i32_e32 v5, 31, v4
	v_lshl_add_u64 v[2:3], v[4:5], 1, v[2:3]
	v_add_u32_e32 v5, 0x200, v0
	v_ashrrev_i32_e32 v4, 31, v5
	v_lshrrev_b32_e32 v4, 27, v4
	v_add_u32_e32 v6, v5, v4
	v_ashrrev_i32_e32 v4, 5, v6
	v_and_b32_e32 v6, 0x1fffffe0, v6
	v_sub_u32_e32 v5, v5, v6
	v_lshlrev_b32_e32 v6, 3, v5
	v_ashrrev_i32_e32 v5, 31, v4
	v_lshl_add_u64 v[4:5], s[12:13], 0, v[4:5]
	v_mad_u64_u32 v[8:9], s[14:15], v4, s33, v[20:21]
	v_mad_i32_i24 v9, v5, s33, v9
	v_add_co_u32_e32 v2, vcc, s34, v2
	v_lshl_add_u64 v[4:5], v[8:9], 0, s[38:39]
	v_ashrrev_i32_e32 v7, 31, v6
	v_addc_co_u32_e32 v3, vcc, 0, v3, vcc
	v_lshl_add_u64 v[4:5], v[6:7], 1, v[4:5]
	v_add_co_u32_e32 v8, vcc, s34, v4
	s_nop 1
	v_addc_co_u32_e32 v9, vcc, 0, v5, vcc
	global_load_dwordx4 v[4:7], v[2:3], off offset:2048
	s_nop 0
	global_load_dwordx4 v[8:11], v[8:9], off offset:2048
	v_add_u32_e32 v3, 0x400, v0
	v_ashrrev_i32_e32 v2, 31, v3
	v_lshrrev_b32_e32 v2, 27, v2
	v_add_u32_e32 v22, v3, v2
	v_ashrrev_i32_e32 v2, 5, v22
	v_and_b32_e32 v22, 0x1fffffe0, v22
	v_sub_u32_e32 v3, v3, v22
	v_lshlrev_b32_e32 v22, 3, v3
	v_ashrrev_i32_e32 v3, 31, v2
	v_lshl_add_u64 v[2:3], s[12:13], 0, v[2:3]
	v_mad_u64_u32 v[24:25], s[14:15], v2, s33, v[20:21]
	v_mad_i32_i24 v25, v3, s33, v25
	v_lshl_add_u64 v[2:3], v[24:25], 0, s[38:39]
	v_ashrrev_i32_e32 v23, 31, v22
	v_add_u32_e32 v0, 0x600, v0
	v_lshl_add_u64 v[2:3], v[22:23], 1, v[2:3]
	v_ashrrev_i32_e32 v22, 31, v0
	v_lshrrev_b32_e32 v22, 27, v22
	v_add_u32_e32 v23, v0, v22
	v_ashrrev_i32_e32 v22, 5, v23
	v_and_b32_e32 v23, 0x1fffffe0, v23
	v_sub_u32_e32 v0, v0, v23
	v_ashrrev_i32_e32 v23, 31, v22
	v_lshl_add_u64 v[22:23], s[12:13], 0, v[22:23]
	v_mad_u64_u32 v[20:21], s[12:13], v22, s33, v[20:21]
	v_lshlrev_b32_e32 v24, 3, v0
	v_mad_i32_i24 v21, v23, s33, v21
	v_add_co_u32_e32 v2, vcc, s34, v2
	v_lshl_add_u64 v[20:21], v[20:21], 0, s[38:39]
	v_ashrrev_i32_e32 v25, 31, v24
	v_addc_co_u32_e32 v3, vcc, 0, v3, vcc
	v_lshl_add_u64 v[20:21], v[24:25], 1, v[20:21]
	v_add_co_u32_e32 v24, vcc, 0x7a00000, v20
	s_nop 1
	v_addc_co_u32_e32 v25, vcc, 0, v21, vcc
	global_load_dwordx4 v[20:23], v[2:3], off offset:2048
	s_nop 0
	global_load_dwordx4 v[24:27], v[24:25], off offset:2048

.LBB0_1737:
	s_or_b64 exec, exec, s[8:9]
	s_add_i32 s49, s47, s22
	s_lshl_b32 s8, s2, 2
	s_add_u32 s8, s26, s8
	s_addc_u32 s9, s27, 0
	v_lshl_add_u32 v8, v131, 2, s96
	v_lshl_add_u64 v[84:85], v[84:85], 2, s[8:9]
	s_waitcnt lgkmcnt(0)
	s_barrier
	ds_read2st64_b32 v[94:95], v8 offset1:1
	ds_read2st64_b32 v[96:97], v8 offset0:2 offset1:3
	ds_read2st64_b32 v[98:99], v8 offset0:4 offset1:5
	ds_read2st64_b32 v[100:101], v8 offset0:6 offset1:7
	global_load_dwordx4 v[252:255], v[84:85], off offset:16
	global_load_dwordx4 v[248:251], v[84:85], off
	s_waitcnt vmcnt(5)
	v_lshlrev_b32_e32 v104, 16, v72
	v_and_b32_e32 v105, 0xffff0000, v72
	v_mul_f32_e32 v8, 0xbfb8aa3b, v104
	v_lshlrev_b64 v[102:103], 11, v[10:11]
	v_exp_f32_e32 v8, v8
	v_mul_f32_e32 v10, 0xbfb8aa3b, v105
	v_exp_f32_e32 v10, v10
	v_lshlrev_b32_e32 v106, 16, v73
	v_add_f32_e32 v8, 1.0, v8
	v_rcp_f32_e32 v72, v8
	v_add_f32_e32 v8, 1.0, v10
	v_mul_f32_e32 v10, 0xbfb8aa3b, v106
	v_exp_f32_e32 v10, v10
	v_and_b32_e32 v107, 0xffff0000, v73
	v_mul_f32_e32 v73, 0xbfb8aa3b, v107
	v_lshlrev_b32_e32 v110, 16, v74
	v_exp_f32_e32 v109, v73
	v_rcp_f32_e32 v73, v8
	v_add_f32_e32 v8, 1.0, v10
	v_and_b32_e32 v111, 0xffff0000, v74
	v_mul_f32_e32 v10, 0xbfb8aa3b, v110
	v_exp_f32_e32 v10, v10
	v_mul_f32_e32 v74, 0xbfb8aa3b, v111
	v_exp_f32_e32 v112, v74
	v_rcp_f32_e32 v108, v8
	v_add_f32_e32 v8, 1.0, v109
	v_rcp_f32_e32 v109, v8
	v_add_f32_e32 v8, 1.0, v10
	v_rcp_f32_e32 v74, v8
	v_add_f32_e32 v8, 1.0, v112
	v_lshlrev_b32_e32 v112, 16, v75
	v_and_b32_e32 v113, 0xffff0000, v75
	v_mul_f32_e32 v10, 0xbfb8aa3b, v112
	v_exp_f32_e32 v10, v10
	v_mul_f32_e32 v75, 0xbfb8aa3b, v113
	v_exp_f32_e32 v115, v75
	v_rcp_f32_e32 v75, v8
	v_add_f32_e32 v8, 1.0, v10
	v_rcp_f32_e32 v114, v8
	v_add_f32_e32 v8, 1.0, v115
	v_rcp_f32_e32 v115, v8
	v_lshl_add_u32 v8, v129, 2, s96
	v_pk_mul_f32 v[106:107], v[108:109], v[106:107]
	v_pk_mul_f32 v[108:109], v[74:75], v[110:111]
	ds_read2st64_b32 v[74:75], v8 offset1:1
	v_pk_mul_f32 v[110:111], v[114:115], v[112:113]
	ds_read2st64_b32 v[112:113], v8 offset0:2 offset1:3
	ds_read2st64_b32 v[114:115], v8 offset0:4 offset1:5
	ds_read2st64_b32 v[116:117], v8 offset0:6 offset1:7
	s_waitcnt lgkmcnt(7)
	v_mov_b32_e32 v119, v94
	v_ashrrev_i32_e32 v133, 31, v132
	s_waitcnt lgkmcnt(3)
	v_mov_b32_e32 v118, v74
	v_pk_add_f32 v[118:119], v[118:119], 0 op_sel_hi:[1,0]
	v_mov_b32_e32 v94, v75
	v_pk_add_f32 v[74:75], v[118:119], v[94:95]
	s_waitcnt lgkmcnt(2)
	v_mov_b32_e32 v94, v112
	v_mov_b32_e32 v95, v96
	v_pk_add_f32 v[74:75], v[74:75], v[94:95]
	v_mov_b32_e32 v96, v113
	v_pk_add_f32 v[74:75], v[74:75], v[96:97]
	s_waitcnt lgkmcnt(1)
	v_mov_b32_e32 v94, v114
	v_mov_b32_e32 v95, v98
	v_pk_add_f32 v[74:75], v[74:75], v[94:95]
	v_mov_b32_e32 v98, v115
	v_pk_add_f32 v[74:75], v[74:75], v[98:99]
	s_waitcnt lgkmcnt(0)
	v_mov_b32_e32 v94, v116
	v_mov_b32_e32 v95, v100
	v_pk_add_f32 v[74:75], v[74:75], v[94:95]
	v_mov_b32_e32 v100, v117
	v_pk_add_f32 v[94:95], v[74:75], v[100:101]
	v_mov_b64_e32 v[74:75], s[48:49]
	v_pk_fma_f32 v[94:95], v[94:95], s[46:47], v[74:75] op_sel_hi:[1,0,0]
	v_lshl_add_u64 v[102:103], s[28:29], 0, v[102:103]
	v_mul_f32_e32 v8, 0x4b800000, v95
	v_cmp_gt_f32_e32 vcc, s45, v95
	s_lshl_b32 s38, s2, 1
	v_pk_mul_f32 v[104:105], v[72:73], v[104:105]
	v_cndmask_b32_e32 v8, v95, v8, vcc
	v_rsq_f32_e32 v8, v8
	v_lshl_add_u64 v[102:103], v[102:103], 0, s[38:39]
	v_lshlrev_b64 v[72:73], 1, v[132:133]
	v_lshl_add_u64 v[96:97], v[102:103], 0, v[72:73]
	v_mul_f32_e32 v10, 0x45800000, v8
	v_cndmask_b32_e32 v8, v8, v10, vcc
	v_pk_mul_f32 v[80:81], v[80:81], v[8:9] op_sel_hi:[1,0]
	v_pk_mul_f32 v[82:83], v[82:83], v[8:9] op_sel_hi:[1,0]
	v_pk_mul_f32 v[76:77], v[76:77], v[8:9] op_sel_hi:[1,0]
	v_pk_mul_f32 v[78:79], v[78:79], v[8:9] op_sel_hi:[1,0]
	s_waitcnt vmcnt(0)
	v_pk_mul_f32 v[80:81], v[248:249], v[80:81]
	v_pk_mul_f32 v[82:83], v[250:251], v[82:83]
	v_pk_mul_f32 v[76:77], v[252:253], v[76:77]
	v_pk_mul_f32 v[78:79], v[254:255], v[78:79]
	v_mov_b32_e32 v127, v9
	v_pk_mul_f32 v[80:81], v[104:105], v[80:81]
	v_pk_mul_f32 v[82:83], v[106:107], v[82:83]
	v_pk_mul_f32 v[76:77], v[108:109], v[76:77]
	v_pk_mul_f32 v[78:79], v[110:111], v[78:79]
	v_lshl_add_u64 v[96:97], v[96:97], 0, v[126:127]
	v_cvt_pk_bf16_f32 v80, v80, v81
	v_cvt_pk_bf16_f32 v81, v82, v83
	v_cvt_pk_bf16_f32 v82, v76, v77
	v_cvt_pk_bf16_f32 v83, v78, v79
	global_store_dwordx4 v[96:97], v[80:83], off
	s_nop 1
	s_nop 0
	s_nop 0
	s_nop 0
	v_lshlrev_b32_e32 v86, 16, v68
	v_and_b32_e32 v87, 0xffff0000, v68
	v_lshlrev_b32_e32 v68, 16, v69
	v_and_b32_e32 v69, 0xffff0000, v69
	v_mul_f32_e32 v8, 0xbfb8aa3b, v86
	v_mul_f32_e32 v92, 0xbfb8aa3b, v69
	v_exp_f32_e32 v8, v8
	v_exp_f32_e32 v92, v92
	v_lshlrev_b32_e32 v88, 16, v70
	v_and_b32_e32 v89, 0xffff0000, v70
	v_mul_f32_e32 v10, 0xbfb8aa3b, v87
	v_mul_f32_e32 v70, 0xbfb8aa3b, v68
	v_add_f32_e32 v8, 1.0, v8
	v_mul_f32_e32 v93, 0xbfb8aa3b, v88
	v_exp_f32_e32 v10, v10
	v_exp_f32_e32 v70, v70
	v_add_f32_e32 v97, 1.0, v92
	v_rcp_f32_e32 v92, v8
	v_mul_f32_e32 v8, 0x4b800000, v94
	v_cmp_gt_f32_e32 vcc, s45, v94
	v_exp_f32_e32 v93, v93
	v_add_f32_e32 v10, 1.0, v10
	v_cndmask_b32_e32 v8, v94, v8, vcc
	v_rsq_f32_e32 v8, v8
	v_add_f32_e32 v70, 1.0, v70
	v_add_f32_e32 v98, 1.0, v93
	v_rcp_f32_e32 v93, v10
	v_rcp_f32_e32 v96, v70
	v_rcp_f32_e32 v97, v97
	v_mul_f32_e32 v10, 0x45800000, v8
	v_cndmask_b32_e32 v8, v8, v10, vcc
	v_pk_mul_f32 v[64:65], v[64:65], v[8:9] op_sel_hi:[1,0]
	v_pk_mul_f32 v[66:67], v[66:67], v[8:9] op_sel_hi:[1,0]
	v_pk_mul_f32 v[86:87], v[92:93], v[86:87]
	v_pk_mul_f32 v[68:69], v[96:97], v[68:69]
	v_pk_mul_f32 v[60:61], v[60:61], v[8:9] op_sel_hi:[1,0]
	v_mul_f32_e32 v95, 0xbfb8aa3b, v89
	v_exp_f32_e32 v95, v95
	v_rcp_f32_e32 v94, v98
	v_mov_b32_e32 v131, v11
	v_pk_mul_f32 v[62:63], v[62:63], v[8:9] op_sel_hi:[1,0]
	v_add_f32_e32 v95, 1.0, v95
	v_rcp_f32_e32 v95, v95
	v_lshlrev_b64 v[90:91], 11, v[130:131]
	v_lshl_add_u64 v[90:91], s[28:29], 0, v[90:91]
	v_lshl_add_u32 v8, v177, 2, s96
	v_mov_b32_e32 v129, v11
	s_add_i32 s3, s3, s88
	s_add_i32 s72, s72, s83
	s_cmpk_gt_i32 s49, 0x3ff
	s_cselect_b64 s[8:9], -1, 0
	s_nop 0
	v_pk_mul_f32 v[64:65], v[248:249], v[64:65]
	v_pk_mul_f32 v[66:67], v[250:251], v[66:67]
	s_nop 0
	v_pk_mul_f32 v[76:77], v[252:253], v[60:61]
	v_pk_mul_f32 v[60:61], v[86:87], v[64:65]
	v_pk_mul_f32 v[64:65], v[68:69], v[66:67]
	v_cvt_pk_bf16_f32 v60, v60, v61
	v_cvt_pk_bf16_f32 v61, v64, v65
	v_lshlrev_b32_e32 v64, 16, v71
	v_and_b32_e32 v65, 0xffff0000, v71
	v_mul_f32_e32 v10, 0xbfb8aa3b, v64
	v_exp_f32_e32 v10, v10
	v_mul_f32_e32 v66, 0xbfb8aa3b, v65
	v_exp_f32_e32 v69, v66
	v_pk_mul_f32 v[62:63], v[254:255], v[62:63]
	v_add_f32_e32 v10, 1.0, v10
	v_rcp_f32_e32 v68, v10
	v_add_f32_e32 v10, 1.0, v69
	v_rcp_f32_e32 v69, v10
	v_pk_mul_f32 v[66:67], v[94:95], v[88:89]
	v_lshlrev_b32_e32 v82, 16, v56
	v_pk_mul_f32 v[66:67], v[66:67], v[76:77]
	v_pk_mul_f32 v[64:65], v[68:69], v[64:65]
	v_and_b32_e32 v83, 0xffff0000, v56
	v_pk_mul_f32 v[64:65], v[64:65], v[62:63]
	v_cvt_pk_bf16_f32 v62, v66, v67
	v_cvt_pk_bf16_f32 v63, v64, v65
	v_lshl_add_u64 v[64:65], v[90:91], 0, s[38:39]
	v_lshl_add_u64 v[64:65], v[64:65], 0, v[72:73]
	v_lshl_add_u64 v[64:65], v[64:65], 0, v[126:127]
	global_store_dwordx4 v[64:65], v[60:63], off
	s_nop 1
	ds_read2st64_b32 v[68:69], v8 offset1:1
	ds_read2st64_b32 v[70:71], v8 offset0:2 offset1:3
	ds_read2st64_b32 v[76:77], v8 offset0:4 offset1:5
	ds_read2st64_b32 v[78:79], v8 offset0:6 offset1:7
	s_nop 0
	s_nop 0
	v_mul_f32_e32 v8, 0xbfb8aa3b, v82
	v_exp_f32_e32 v8, v8
	v_mul_f32_e32 v10, 0xbfb8aa3b, v83
	v_exp_f32_e32 v10, v10
	v_lshlrev_b32_e32 v56, 16, v57
	v_add_f32_e32 v8, 1.0, v8
	v_rcp_f32_e32 v86, v8
	v_add_f32_e32 v8, 1.0, v10
	v_rcp_f32_e32 v87, v8
	v_and_b32_e32 v57, 0xffff0000, v57
	v_mul_f32_e32 v8, 0xbfb8aa3b, v56
	v_exp_f32_e32 v8, v8
	v_mul_f32_e32 v10, 0xbfb8aa3b, v57
	v_exp_f32_e32 v10, v10
	v_pk_mul_f32 v[82:83], v[86:87], v[82:83]
	v_add_f32_e32 v8, 1.0, v8
	v_rcp_f32_e32 v86, v8
	v_add_f32_e32 v8, 1.0, v10
	v_lshlrev_b32_e32 v88, 16, v58
	v_rcp_f32_e32 v87, v8
	v_and_b32_e32 v89, 0xffff0000, v58
	v_mul_f32_e32 v8, 0xbfb8aa3b, v88
	v_exp_f32_e32 v8, v8
	v_mul_f32_e32 v10, 0xbfb8aa3b, v89
	v_exp_f32_e32 v10, v10
	v_pk_mul_f32 v[56:57], v[86:87], v[56:57]
	v_add_f32_e32 v8, 1.0, v8
	v_lshlrev_b32_e32 v86, 16, v59
	v_rcp_f32_e32 v58, v8
	v_add_f32_e32 v8, 1.0, v10
	v_and_b32_e32 v87, 0xffff0000, v59
	v_mul_f32_e32 v10, 0xbfb8aa3b, v86
	v_exp_f32_e32 v10, v10
	v_mul_f32_e32 v59, 0xbfb8aa3b, v87
	v_exp_f32_e32 v91, v59
	v_rcp_f32_e32 v59, v8
	v_add_f32_e32 v8, 1.0, v10
	v_rcp_f32_e32 v90, v8
	v_add_f32_e32 v8, 1.0, v91
	v_rcp_f32_e32 v91, v8
	v_lshl_add_u32 v8, v125, 2, s96
	v_pk_mul_f32 v[58:59], v[58:59], v[88:89]
	ds_read2st64_b32 v[88:89], v8 offset1:1
	v_pk_mul_f32 v[86:87], v[90:91], v[86:87]
	ds_read2st64_b32 v[90:91], v8 offset0:2 offset1:3
	ds_read2st64_b32 v[92:93], v8 offset0:4 offset1:5
	ds_read2st64_b32 v[94:95], v8 offset0:6 offset1:7
	s_waitcnt lgkmcnt(7)
	v_mov_b32_e32 v97, v68
	v_lshlrev_b64 v[80:81], 11, v[128:129]
	s_waitcnt lgkmcnt(3)
	v_mov_b32_e32 v96, v88
	v_pk_add_f32 v[96:97], v[96:97], 0 op_sel_hi:[1,0]
	v_mov_b32_e32 v68, v89
	v_pk_add_f32 v[68:69], v[96:97], v[68:69]
	s_waitcnt lgkmcnt(2)
	v_mov_b32_e32 v88, v90
	v_mov_b32_e32 v89, v70
	v_pk_add_f32 v[68:69], v[68:69], v[88:89]
	v_mov_b32_e32 v70, v91
	v_pk_add_f32 v[68:69], v[68:69], v[70:71]
	s_waitcnt lgkmcnt(1)
	v_mov_b32_e32 v70, v92
	v_mov_b32_e32 v71, v76
	v_pk_add_f32 v[68:69], v[68:69], v[70:71]
	v_mov_b32_e32 v76, v93
	v_pk_add_f32 v[68:69], v[68:69], v[76:77]
	s_waitcnt lgkmcnt(0)
	v_mov_b32_e32 v70, v94
	v_mov_b32_e32 v71, v78
	v_pk_add_f32 v[68:69], v[68:69], v[70:71]
	v_mov_b32_e32 v78, v95
	v_pk_add_f32 v[68:69], v[68:69], v[78:79]
	v_lshl_add_u64 v[80:81], s[28:29], 0, v[80:81]
	v_pk_fma_f32 v[68:69], v[68:69], s[46:47], v[74:75] op_sel_hi:[1,0,0]
	v_lshl_add_u64 v[70:71], v[80:81], 0, s[38:39]
	v_mul_f32_e32 v8, 0x4b800000, v69
	v_cmp_gt_f32_e32 vcc, s45, v69
	v_lshl_add_u64 v[70:71], v[70:71], 0, v[72:73]
	v_lshl_add_u64 v[70:71], v[70:71], 0, v[126:127]
	v_cndmask_b32_e32 v8, v69, v8, vcc
	v_rsq_f32_e32 v8, v8
	v_mov_b32_e32 v125, v11
	v_and_b32_e32 v11, 0xffff0000, v44
	v_mul_f32_e32 v10, 0x45800000, v8
	v_cndmask_b32_e32 v8, v8, v10, vcc
	v_pk_mul_f32 v[52:53], v[52:53], v[8:9] op_sel_hi:[1,0]
	v_pk_mul_f32 v[54:55], v[54:55], v[8:9] op_sel_hi:[1,0]
	v_pk_mul_f32 v[48:49], v[48:49], v[8:9] op_sel_hi:[1,0]
	v_pk_mul_f32 v[50:51], v[50:51], v[8:9] op_sel_hi:[1,0]
	s_nop 0
	v_pk_mul_f32 v[52:53], v[248:249], v[52:53]
	v_pk_mul_f32 v[54:55], v[250:251], v[54:55]
	v_pk_mul_f32 v[48:49], v[252:253], v[48:49]
	v_pk_mul_f32 v[50:51], v[254:255], v[50:51]
	v_pk_mul_f32 v[52:53], v[82:83], v[52:53]
	v_pk_mul_f32 v[54:55], v[56:57], v[54:55]
	v_pk_mul_f32 v[48:49], v[58:59], v[48:49]
	v_pk_mul_f32 v[50:51], v[86:87], v[50:51]
	v_cvt_pk_bf16_f32 v52, v52, v53
	v_cvt_pk_bf16_f32 v53, v54, v55
	v_cvt_pk_bf16_f32 v54, v48, v49
	v_cvt_pk_bf16_f32 v55, v50, v51
	global_store_dwordx4 v[70:71], v[52:55], off
	s_nop 1
	s_nop 0
	s_nop 0
	s_nop 0
	v_lshlrev_b32_e32 v10, 16, v44
	v_mul_f32_e32 v8, 0xbfb8aa3b, v10
	v_mul_f32_e32 v58, 0xbfb8aa3b, v11
	v_exp_f32_e32 v8, v8
	v_lshlrev_b32_e32 v44, 16, v45
	v_exp_f32_e32 v58, v58
	v_mul_f32_e32 v59, 0xbfb8aa3b, v44
	v_and_b32_e32 v45, 0xffff0000, v45
	v_exp_f32_e32 v59, v59
	v_mul_f32_e32 v60, 0xbfb8aa3b, v45
	v_add_f32_e32 v8, 1.0, v8
	v_exp_f32_e32 v60, v60
	v_add_f32_e32 v61, 1.0, v58
	v_rcp_f32_e32 v58, v8
	v_mul_f32_e32 v8, 0x4b800000, v68
	v_cmp_gt_f32_e32 vcc, s45, v68
	v_add_f32_e32 v62, 1.0, v59
	v_rcp_f32_e32 v59, v61
	v_cndmask_b32_e32 v8, v68, v8, vcc
	v_rsq_f32_e32 v8, v8
	v_add_f32_e32 v63, 1.0, v60
	v_rcp_f32_e32 v60, v62
	v_rcp_f32_e32 v61, v63
	v_pk_mul_f32 v[10:11], v[58:59], v[10:11]
	v_mul_f32_e32 v58, 0x45800000, v8
	v_cndmask_b32_e32 v8, v8, v58, vcc
	v_pk_mul_f32 v[42:43], v[42:43], v[8:9] op_sel_hi:[1,0]
	v_pk_mul_f32 v[44:45], v[60:61], v[44:45]
	v_pk_mul_f32 v[40:41], v[40:41], v[8:9] op_sel_hi:[1,0]
	v_pk_mul_f32 v[36:37], v[36:37], v[8:9] op_sel_hi:[1,0]
	v_lshlrev_b64 v[56:57], 11, v[124:125]
	v_lshl_add_u64 v[56:57], s[28:29], 0, v[56:57]
	s_nop 0
	v_pk_mul_f32 v[42:43], v[250:251], v[42:43]
	v_pk_mul_f32 v[40:41], v[248:249], v[40:41]
	v_pk_mul_f32 v[42:43], v[44:45], v[42:43]
	v_lshlrev_b32_e32 v44, 16, v46
	v_pk_mul_f32 v[10:11], v[10:11], v[40:41]
	v_mul_f32_e32 v40, 0xbfb8aa3b, v44
	v_and_b32_e32 v45, 0xffff0000, v46
	v_exp_f32_e32 v48, v40
	v_cvt_pk_bf16_f32 v40, v10, v11
	v_mul_f32_e32 v11, 0xbfb8aa3b, v45
	v_exp_f32_e32 v11, v11
	v_cvt_pk_bf16_f32 v41, v42, v43
	v_lshlrev_b32_e32 v42, 16, v47
	v_and_b32_e32 v43, 0xffff0000, v47
	v_add_f32_e32 v10, 1.0, v48
	v_add_f32_e32 v11, 1.0, v11
	v_mul_f32_e32 v46, 0xbfb8aa3b, v42
	v_mul_f32_e32 v47, 0xbfb8aa3b, v43
	v_rcp_f32_e32 v10, v10
	v_rcp_f32_e32 v11, v11
	v_exp_f32_e32 v46, v46
	v_exp_f32_e32 v47, v47
	s_nop 0
	v_pk_mul_f32 v[36:37], v[252:253], v[36:37]
	v_pk_mul_f32 v[10:11], v[10:11], v[44:45]
	v_add_f32_e32 v44, 1.0, v46
	v_add_f32_e32 v45, 1.0, v47
	v_rcp_f32_e32 v44, v44
	v_rcp_f32_e32 v45, v45
	v_pk_mul_f32 v[10:11], v[10:11], v[36:37]
	v_pk_mul_f32 v[36:37], v[38:39], v[8:9] op_sel_hi:[1,0]
	v_pk_mul_f32 v[38:39], v[44:45], v[42:43]
	v_pk_mul_f32 v[36:37], v[254:255], v[36:37]
	v_cvt_pk_bf16_f32 v42, v10, v11
	v_lshl_add_u64 v[10:11], v[56:57], 0, s[38:39]
	v_pk_mul_f32 v[36:37], v[38:39], v[36:37]
	v_lshl_add_u64 v[10:11], v[10:11], 0, v[72:73]
	v_cvt_pk_bf16_f32 v43, v36, v37
	v_lshl_add_u64 v[10:11], v[10:11], 0, v[126:127]
	global_store_dwordx4 v[10:11], v[40:43], off
	s_nop 1
	s_nop 0

.LBB0_1777:
	s_or_b64 exec, exec, s[8:9]
	s_lshl_b32 s8, s2, 2
	s_add_u32 s8, s26, s8
	s_addc_u32 s9, s27, 0
	v_lshl_add_u32 v8, v131, 2, s96
	v_lshl_add_u64 v[84:85], v[84:85], 2, s[8:9]
	s_waitcnt lgkmcnt(0)
	s_barrier
	ds_read2st64_b32 v[94:95], v8 offset1:1
	ds_read2st64_b32 v[96:97], v8 offset0:2 offset1:3
	ds_read2st64_b32 v[98:99], v8 offset0:4 offset1:5
	ds_read2st64_b32 v[100:101], v8 offset0:6 offset1:7
	global_load_dwordx4 v[252:255], v[84:85], off offset:16
	global_load_dwordx4 v[248:251], v[84:85], off
	s_waitcnt vmcnt(5)
	v_lshlrev_b32_e32 v104, 16, v72
	v_and_b32_e32 v105, 0xffff0000, v72
	v_mul_f32_e32 v8, 0xbfb8aa3b, v104
	v_exp_f32_e32 v8, v8
	v_mul_f32_e32 v72, 0xbfb8aa3b, v105
	v_exp_f32_e32 v106, v72
	v_and_b32_e32 v107, 0xffff0000, v73
	v_add_f32_e32 v8, 1.0, v8
	v_rcp_f32_e32 v72, v8
	v_add_f32_e32 v8, 1.0, v106
	v_lshlrev_b32_e32 v106, 16, v73
	v_mul_f32_e32 v73, 0xbfb8aa3b, v106
	v_exp_f32_e32 v108, v73
	v_mul_f32_e32 v73, 0xbfb8aa3b, v107
	v_exp_f32_e32 v109, v73
	v_lshlrev_b32_e32 v110, 16, v74
	v_rcp_f32_e32 v73, v8
	v_add_f32_e32 v8, 1.0, v108
	v_and_b32_e32 v111, 0xffff0000, v74
	v_mul_f32_e32 v74, 0xbfb8aa3b, v110
	v_rcp_f32_e32 v108, v8
	v_add_f32_e32 v8, 1.0, v109
	v_exp_f32_e32 v74, v74
	v_mul_f32_e32 v109, 0xbfb8aa3b, v111
	v_exp_f32_e32 v112, v109
	v_rcp_f32_e32 v109, v8
	v_add_f32_e32 v8, 1.0, v74
	v_rcp_f32_e32 v74, v8
	v_add_f32_e32 v8, 1.0, v112
	v_lshlrev_b32_e32 v112, 16, v75
	v_and_b32_e32 v113, 0xffff0000, v75
	v_mul_f32_e32 v75, 0xbfb8aa3b, v112
	v_exp_f32_e32 v114, v75
	v_mul_f32_e32 v75, 0xbfb8aa3b, v113
	v_exp_f32_e32 v115, v75
	v_rcp_f32_e32 v75, v8
	v_add_f32_e32 v8, 1.0, v114
	v_rcp_f32_e32 v114, v8
	v_add_f32_e32 v8, 1.0, v115
	v_rcp_f32_e32 v115, v8
	v_lshl_add_u32 v8, v129, 2, s96
	v_pk_mul_f32 v[106:107], v[108:109], v[106:107]
	v_pk_mul_f32 v[108:109], v[74:75], v[110:111]
	ds_read2st64_b32 v[74:75], v8 offset1:1
	v_pk_mul_f32 v[110:111], v[114:115], v[112:113]
	ds_read2st64_b32 v[112:113], v8 offset0:2 offset1:3
	ds_read2st64_b32 v[114:115], v8 offset0:4 offset1:5
	ds_read2st64_b32 v[116:117], v8 offset0:6 offset1:7
	s_waitcnt lgkmcnt(7)
	v_mov_b32_e32 v119, v94
	v_lshlrev_b64 v[102:103], 11, v[124:125]
	s_waitcnt lgkmcnt(3)
	v_mov_b32_e32 v118, v74
	v_pk_add_f32 v[118:119], v[118:119], 0 op_sel_hi:[1,0]
	v_mov_b32_e32 v94, v75
	v_pk_add_f32 v[74:75], v[118:119], v[94:95]
	s_waitcnt lgkmcnt(2)
	v_mov_b32_e32 v94, v112
	v_mov_b32_e32 v95, v96
	v_pk_add_f32 v[74:75], v[74:75], v[94:95]
	v_mov_b32_e32 v96, v113
	v_pk_add_f32 v[74:75], v[74:75], v[96:97]
	s_waitcnt lgkmcnt(1)
	v_mov_b32_e32 v94, v114
	v_mov_b32_e32 v95, v98
	v_pk_add_f32 v[74:75], v[74:75], v[94:95]
	v_mov_b32_e32 v98, v115
	v_pk_add_f32 v[74:75], v[74:75], v[98:99]
	s_waitcnt lgkmcnt(0)
	v_mov_b32_e32 v94, v116
	v_mov_b32_e32 v95, v100
	v_pk_add_f32 v[74:75], v[74:75], v[94:95]
	v_mov_b32_e32 v100, v117
	v_pk_add_f32 v[94:95], v[74:75], v[100:101]
	v_mov_b64_e32 v[74:75], s[48:49]
	v_pk_fma_f32 v[94:95], v[94:95], s[46:47], v[74:75] op_sel_hi:[1,0,0]
	v_ashrrev_i32_e32 v133, 31, v132
	v_mul_f32_e32 v8, 0x4b800000, v95
	v_cmp_gt_f32_e32 vcc, s45, v95
	v_lshl_add_u64 v[102:103], s[28:29], 0, v[102:103]
	s_lshl_b32 s38, s2, 1
	v_cndmask_b32_e32 v8, v95, v8, vcc
	v_rsq_f32_e32 v8, v8
	v_pk_mul_f32 v[104:105], v[72:73], v[104:105]
	v_lshl_add_u64 v[102:103], v[102:103], 0, s[38:39]
	v_lshlrev_b64 v[72:73], 1, v[132:133]
	v_mul_f32_e32 v95, 0x45800000, v8
	v_cndmask_b32_e32 v8, v8, v95, vcc
	v_pk_mul_f32 v[80:81], v[80:81], v[8:9] op_sel_hi:[1,0]
	v_pk_mul_f32 v[82:83], v[82:83], v[8:9] op_sel_hi:[1,0]
	v_pk_mul_f32 v[76:77], v[76:77], v[8:9] op_sel_hi:[1,0]
	v_pk_mul_f32 v[78:79], v[78:79], v[8:9] op_sel_hi:[1,0]
	s_waitcnt vmcnt(0)
	v_pk_mul_f32 v[80:81], v[248:249], v[80:81]
	v_pk_mul_f32 v[82:83], v[250:251], v[82:83]
	v_pk_mul_f32 v[76:77], v[252:253], v[76:77]
	v_pk_mul_f32 v[78:79], v[254:255], v[78:79]
	v_lshl_add_u64 v[96:97], v[102:103], 0, v[72:73]
	v_mov_b32_e32 v127, v9
	v_pk_mul_f32 v[80:81], v[104:105], v[80:81]
	v_pk_mul_f32 v[82:83], v[106:107], v[82:83]
	v_pk_mul_f32 v[76:77], v[108:109], v[76:77]
	v_pk_mul_f32 v[78:79], v[110:111], v[78:79]
	v_lshl_add_u64 v[96:97], v[96:97], 0, v[126:127]
	v_cvt_pk_bf16_f32 v80, v80, v81
	v_cvt_pk_bf16_f32 v81, v82, v83
	v_cvt_pk_bf16_f32 v82, v76, v77
	v_cvt_pk_bf16_f32 v83, v78, v79
	global_store_dwordx4 v[96:97], v[80:83], off
	s_nop 1
	s_nop 0
	s_nop 0
	s_nop 0
	v_lshlrev_b32_e32 v86, 16, v68
	v_and_b32_e32 v87, 0xffff0000, v68
	v_lshlrev_b32_e32 v68, 16, v69
	v_mul_f32_e32 v8, 0xbfb8aa3b, v86
	v_mul_f32_e32 v92, 0xbfb8aa3b, v68
	v_exp_f32_e32 v8, v8
	v_exp_f32_e32 v92, v92
	v_and_b32_e32 v69, 0xffff0000, v69
	v_lshlrev_b32_e32 v88, 16, v70
	v_and_b32_e32 v89, 0xffff0000, v70
	v_mul_f32_e32 v70, 0xbfb8aa3b, v87
	v_mul_f32_e32 v93, 0xbfb8aa3b, v69
	v_add_f32_e32 v8, 1.0, v8
	v_mul_f32_e32 v96, 0xbfb8aa3b, v89
	v_exp_f32_e32 v70, v70
	v_exp_f32_e32 v93, v93
	v_add_f32_e32 v97, 1.0, v92
	v_rcp_f32_e32 v92, v8
	v_mul_f32_e32 v8, 0x4b800000, v94
	v_cmp_gt_f32_e32 vcc, s45, v94
	v_exp_f32_e32 v96, v96
	v_add_f32_e32 v70, 1.0, v70
	v_cndmask_b32_e32 v8, v94, v8, vcc
	v_rsq_f32_e32 v8, v8
	v_add_f32_e32 v98, 1.0, v93
	v_add_f32_e32 v99, 1.0, v96
	v_rcp_f32_e32 v93, v70
	v_rcp_f32_e32 v96, v97
	v_rcp_f32_e32 v97, v98
	v_mul_f32_e32 v70, 0x45800000, v8
	v_cndmask_b32_e32 v8, v8, v70, vcc
	v_pk_mul_f32 v[64:65], v[64:65], v[8:9] op_sel_hi:[1,0]
	v_pk_mul_f32 v[66:67], v[66:67], v[8:9] op_sel_hi:[1,0]
	v_pk_mul_f32 v[86:87], v[92:93], v[86:87]
	v_pk_mul_f32 v[68:69], v[96:97], v[68:69]
	v_pk_mul_f32 v[60:61], v[60:61], v[8:9] op_sel_hi:[1,0]
	v_mul_f32_e32 v95, 0xbfb8aa3b, v88
	v_exp_f32_e32 v95, v95
	v_rcp_f32_e32 v99, v99
	v_mov_b32_e32 v131, v125
	v_pk_mul_f32 v[62:63], v[62:63], v[8:9] op_sel_hi:[1,0]
	v_add_f32_e32 v95, 1.0, v95
	v_rcp_f32_e32 v98, v95
	v_lshlrev_b64 v[90:91], 11, v[130:131]
	v_lshl_add_u64 v[90:91], s[28:29], 0, v[90:91]
	v_lshl_add_u32 v8, v177, 2, s96
	v_mov_b32_e32 v129, v125
	s_cmpk_gt_i32 s47, 0x3ff
	s_mov_b64 s[8:9], -1
	s_nop 0
	v_pk_mul_f32 v[64:65], v[248:249], v[64:65]
	v_pk_mul_f32 v[66:67], v[250:251], v[66:67]
	s_nop 0
	v_pk_mul_f32 v[76:77], v[252:253], v[60:61]
	v_pk_mul_f32 v[60:61], v[86:87], v[64:65]
	v_pk_mul_f32 v[64:65], v[68:69], v[66:67]
	v_cvt_pk_bf16_f32 v60, v60, v61
	v_cvt_pk_bf16_f32 v61, v64, v65
	v_lshlrev_b32_e32 v64, 16, v71
	v_and_b32_e32 v65, 0xffff0000, v71
	v_mul_f32_e32 v66, 0xbfb8aa3b, v64
	v_exp_f32_e32 v68, v66
	v_mul_f32_e32 v66, 0xbfb8aa3b, v65
	v_exp_f32_e32 v69, v66
	v_pk_mul_f32 v[62:63], v[254:255], v[62:63]
	v_add_f32_e32 v68, 1.0, v68
	v_rcp_f32_e32 v68, v68
	v_add_f32_e32 v69, 1.0, v69
	v_rcp_f32_e32 v69, v69
	v_pk_mul_f32 v[66:67], v[98:99], v[88:89]
	v_lshlrev_b32_e32 v82, 16, v56
	v_pk_mul_f32 v[66:67], v[66:67], v[76:77]
	v_pk_mul_f32 v[64:65], v[68:69], v[64:65]
	v_and_b32_e32 v83, 0xffff0000, v56
	v_pk_mul_f32 v[64:65], v[64:65], v[62:63]
	v_cvt_pk_bf16_f32 v62, v66, v67
	v_cvt_pk_bf16_f32 v63, v64, v65
	v_lshl_add_u64 v[64:65], v[90:91], 0, s[38:39]
	v_lshl_add_u64 v[64:65], v[64:65], 0, v[72:73]
	v_lshl_add_u64 v[64:65], v[64:65], 0, v[126:127]
	global_store_dwordx4 v[64:65], v[60:63], off
	s_nop 1
	ds_read2st64_b32 v[68:69], v8 offset1:1
	ds_read2st64_b32 v[70:71], v8 offset0:2 offset1:3
	ds_read2st64_b32 v[76:77], v8 offset0:4 offset1:5
	ds_read2st64_b32 v[78:79], v8 offset0:6 offset1:7
	s_nop 0
	s_nop 0
	v_mul_f32_e32 v8, 0xbfb8aa3b, v82
	v_exp_f32_e32 v8, v8
	v_mul_f32_e32 v56, 0xbfb8aa3b, v83
	v_exp_f32_e32 v56, v56
	v_and_b32_e32 v89, 0xffff0000, v58
	v_add_f32_e32 v8, 1.0, v8
	v_rcp_f32_e32 v86, v8
	v_add_f32_e32 v8, 1.0, v56
	v_lshlrev_b32_e32 v56, 16, v57
	v_rcp_f32_e32 v87, v8
	v_and_b32_e32 v57, 0xffff0000, v57
	v_mul_f32_e32 v8, 0xbfb8aa3b, v56
	v_exp_f32_e32 v8, v8
	v_mul_f32_e32 v88, 0xbfb8aa3b, v57
	v_exp_f32_e32 v88, v88
	v_pk_mul_f32 v[82:83], v[86:87], v[82:83]
	v_add_f32_e32 v8, 1.0, v8
	v_rcp_f32_e32 v86, v8
	v_add_f32_e32 v8, 1.0, v88
	v_lshlrev_b32_e32 v88, 16, v58
	v_rcp_f32_e32 v87, v8
	v_mul_f32_e32 v8, 0xbfb8aa3b, v88
	v_exp_f32_e32 v8, v8
	v_mul_f32_e32 v58, 0xbfb8aa3b, v89
	v_exp_f32_e32 v90, v58
	v_pk_mul_f32 v[56:57], v[86:87], v[56:57]
	v_lshlrev_b32_e32 v86, 16, v59
	v_add_f32_e32 v8, 1.0, v8
	v_and_b32_e32 v87, 0xffff0000, v59
	v_mul_f32_e32 v59, 0xbfb8aa3b, v86
	v_rcp_f32_e32 v58, v8
	v_add_f32_e32 v8, 1.0, v90
	v_exp_f32_e32 v90, v59
	v_mul_f32_e32 v59, 0xbfb8aa3b, v87
	v_exp_f32_e32 v91, v59
	v_rcp_f32_e32 v59, v8
	v_add_f32_e32 v8, 1.0, v90
	v_rcp_f32_e32 v90, v8
	v_add_f32_e32 v8, 1.0, v91
	v_rcp_f32_e32 v91, v8
	v_lshl_add_u32 v8, v11, 2, s96
	v_pk_mul_f32 v[58:59], v[58:59], v[88:89]
	ds_read2st64_b32 v[88:89], v8 offset1:1
	v_pk_mul_f32 v[86:87], v[90:91], v[86:87]
	ds_read2st64_b32 v[90:91], v8 offset0:2 offset1:3
	ds_read2st64_b32 v[92:93], v8 offset0:4 offset1:5
	ds_read2st64_b32 v[94:95], v8 offset0:6 offset1:7
	s_waitcnt lgkmcnt(7)
	v_mov_b32_e32 v97, v68
	v_lshlrev_b64 v[80:81], 11, v[128:129]
	s_waitcnt lgkmcnt(3)
	v_mov_b32_e32 v96, v88
	v_pk_add_f32 v[96:97], v[96:97], 0 op_sel_hi:[1,0]
	v_mov_b32_e32 v68, v89
	v_pk_add_f32 v[68:69], v[96:97], v[68:69]
	s_waitcnt lgkmcnt(2)
	v_mov_b32_e32 v88, v90
	v_mov_b32_e32 v89, v70
	v_pk_add_f32 v[68:69], v[68:69], v[88:89]
	v_mov_b32_e32 v70, v91
	v_pk_add_f32 v[68:69], v[68:69], v[70:71]
	s_waitcnt lgkmcnt(1)
	v_mov_b32_e32 v70, v92
	v_mov_b32_e32 v71, v76
	v_pk_add_f32 v[68:69], v[68:69], v[70:71]
	v_mov_b32_e32 v76, v93
	v_pk_add_f32 v[68:69], v[68:69], v[76:77]
	s_waitcnt lgkmcnt(0)
	v_mov_b32_e32 v70, v94
	v_mov_b32_e32 v71, v78
	v_pk_add_f32 v[68:69], v[68:69], v[70:71]
	v_mov_b32_e32 v78, v95
	v_pk_add_f32 v[68:69], v[68:69], v[78:79]
	v_lshl_add_u64 v[80:81], s[28:29], 0, v[80:81]
	v_pk_fma_f32 v[68:69], v[68:69], s[46:47], v[74:75] op_sel_hi:[1,0,0]
	v_lshl_add_u64 v[70:71], v[80:81], 0, s[38:39]
	v_mul_f32_e32 v8, 0x4b800000, v69
	v_cmp_gt_f32_e32 vcc, s45, v69
	v_lshl_add_u64 v[70:71], v[70:71], 0, v[72:73]
	v_lshl_add_u64 v[70:71], v[70:71], 0, v[126:127]
	v_cndmask_b32_e32 v8, v69, v8, vcc
	v_rsq_f32_e32 v8, v8
	s_nop 0
	v_mul_f32_e32 v11, 0x45800000, v8
	v_cndmask_b32_e32 v8, v8, v11, vcc
	v_pk_mul_f32 v[52:53], v[52:53], v[8:9] op_sel_hi:[1,0]
	v_pk_mul_f32 v[54:55], v[54:55], v[8:9] op_sel_hi:[1,0]
	v_pk_mul_f32 v[48:49], v[48:49], v[8:9] op_sel_hi:[1,0]
	v_pk_mul_f32 v[50:51], v[50:51], v[8:9] op_sel_hi:[1,0]
	s_nop 0
	v_pk_mul_f32 v[52:53], v[248:249], v[52:53]
	v_pk_mul_f32 v[54:55], v[250:251], v[54:55]
	v_pk_mul_f32 v[48:49], v[252:253], v[48:49]
	v_pk_mul_f32 v[50:51], v[254:255], v[50:51]
	v_pk_mul_f32 v[52:53], v[82:83], v[52:53]
	v_pk_mul_f32 v[54:55], v[56:57], v[54:55]
	v_pk_mul_f32 v[48:49], v[58:59], v[48:49]
	v_pk_mul_f32 v[50:51], v[86:87], v[50:51]
	v_cvt_pk_bf16_f32 v52, v52, v53
	v_cvt_pk_bf16_f32 v53, v54, v55
	v_cvt_pk_bf16_f32 v54, v48, v49
	v_cvt_pk_bf16_f32 v55, v50, v51
	global_store_dwordx4 v[70:71], v[52:55], off
	s_nop 1
	s_nop 0
	s_nop 0
	s_nop 0
	v_lshlrev_b32_e32 v56, 16, v44
	v_and_b32_e32 v57, 0xffff0000, v44
	v_lshlrev_b32_e32 v44, 16, v45
	v_mul_f32_e32 v8, 0xbfb8aa3b, v56
	v_mul_f32_e32 v60, 0xbfb8aa3b, v44
	v_exp_f32_e32 v8, v8
	v_exp_f32_e32 v60, v60
	v_and_b32_e32 v45, 0xffff0000, v45
	v_mul_f32_e32 v61, 0xbfb8aa3b, v45
	v_add_f32_e32 v8, 1.0, v8
	v_mul_f32_e32 v59, 0xbfb8aa3b, v57
	v_exp_f32_e32 v61, v61
	v_add_f32_e32 v62, 1.0, v60
	v_rcp_f32_e32 v60, v8
	v_mul_f32_e32 v8, 0x4b800000, v68
	v_cmp_gt_f32_e32 vcc, s45, v68
	v_exp_f32_e32 v59, v59
	v_add_f32_e32 v63, 1.0, v61
	v_cndmask_b32_e32 v8, v68, v8, vcc
	v_rsq_f32_e32 v8, v8
	v_add_f32_e32 v59, 1.0, v59
	v_rcp_f32_e32 v62, v62
	v_rcp_f32_e32 v63, v63
	v_rcp_f32_e32 v61, v59
	v_mul_f32_e32 v59, 0x45800000, v8
	v_cndmask_b32_e32 v8, v8, v59, vcc
	v_pk_mul_f32 v[42:43], v[42:43], v[8:9] op_sel_hi:[1,0]
	v_lshlrev_b32_e32 v58, 16, v46
	v_pk_mul_f32 v[44:45], v[62:63], v[44:45]
	v_pk_mul_f32 v[40:41], v[40:41], v[8:9] op_sel_hi:[1,0]
	v_pk_mul_f32 v[56:57], v[60:61], v[56:57]
	v_and_b32_e32 v59, 0xffff0000, v46
	v_mov_b32_e32 v11, v125
	v_lshlrev_b64 v[10:11], 11, v[10:11]
	v_pk_mul_f32 v[36:37], v[36:37], v[8:9] op_sel_hi:[1,0]
	v_lshl_add_u64 v[10:11], s[28:29], 0, v[10:11]
	v_pk_mul_f32 v[38:39], v[38:39], v[8:9] op_sel_hi:[1,0]
	v_lshl_add_u64 v[10:11], v[10:11], 0, s[38:39]
	v_lshl_add_u64 v[10:11], v[10:11], 0, v[72:73]
	v_lshl_add_u64 v[10:11], v[10:11], 0, v[126:127]
	s_nop 0
	v_pk_mul_f32 v[42:43], v[250:251], v[42:43]
	s_nop 0
	v_pk_mul_f32 v[42:43], v[44:45], v[42:43]
	v_mul_f32_e32 v44, 0xbfb8aa3b, v58
	v_exp_f32_e32 v44, v44
	v_pk_mul_f32 v[40:41], v[248:249], v[40:41]
	v_and_b32_e32 v45, 0xffff0000, v47
	v_pk_mul_f32 v[40:41], v[56:57], v[40:41]
	s_nop 0
	v_pk_mul_f32 v[36:37], v[252:253], v[36:37]
	v_cvt_pk_bf16_f32 v40, v40, v41
	v_cvt_pk_bf16_f32 v41, v42, v43
	v_add_f32_e32 v42, 1.0, v44
	v_mul_f32_e32 v43, 0xbfb8aa3b, v59
	v_lshlrev_b32_e32 v44, 16, v47
	v_exp_f32_e32 v43, v43
	v_mul_f32_e32 v46, 0xbfb8aa3b, v44
	v_mul_f32_e32 v47, 0xbfb8aa3b, v45
	v_exp_f32_e32 v46, v46
	v_exp_f32_e32 v47, v47
	v_add_f32_e32 v43, 1.0, v43
	v_rcp_f32_e32 v42, v42
	v_rcp_f32_e32 v43, v43
	v_add_f32_e32 v46, 1.0, v46
	v_add_f32_e32 v47, 1.0, v47
	v_rcp_f32_e32 v46, v46
	v_rcp_f32_e32 v47, v47
	v_pk_mul_f32 v[42:43], v[42:43], v[58:59]
	v_pk_mul_f32 v[38:39], v[254:255], v[38:39]
	v_pk_mul_f32 v[36:37], v[42:43], v[36:37]
	v_pk_mul_f32 v[42:43], v[46:47], v[44:45]
	s_nop 0
	v_pk_mul_f32 v[38:39], v[42:43], v[38:39]
	v_cvt_pk_bf16_f32 v42, v36, v37
	v_cvt_pk_bf16_f32 v43, v38, v39
	global_store_dwordx4 v[10:11], v[40:43], off
	s_nop 1
	s_nop 0
	s_cbranch_scc1 .LBB0_1738
	s_add_i32 s2, s89, s49
	s_cmpk_gt_i32 s2, 0x3ff
	s_cbranch_scc1 .LBB0_1780
	v_mov_b32_e32 v8, v204
	s_ashr_i32 s8, s2, 8
	s_ashr_i32 s9, s8, 31
	v_ashrrev_i32_e32 v0, 31, v8
	s_add_i32 s2, s88, s3
	v_lshrrev_b32_e32 v0, 27, v0
	s_lshl_b64 s[8:9], s[8:9], 12
	s_and_b32 s2, s2, 0xfc0
	v_add_u32_e32 v1, v8, v0
	s_or_b32 s2, s8, s2
	v_ashrrev_i32_e32 v0, 5, v1
	v_and_b32_e32 v1, 0x1fffffe0, v1
	s_add_u32 s8, s2, 0x4000
	v_sub_u32_e32 v1, v8, v1
	s_addc_u32 s9, s9, 0
	v_lshlrev_b32_e32 v2, 3, v1
	v_ashrrev_i32_e32 v1, 31, v0
	v_add_u32_e32 v13, 0x400, v8
	s_add_i32 s2, s83, s72
	v_lshl_add_u64 v[0:1], s[8:9], 0, v[0:1]
	v_mov_b64_e32 v[10:11], s[30:31]
	v_ashrrev_i32_e32 v12, 31, v13
	s_and_b32 s2, s2, 0x300
	v_mad_u64_u32 v[4:5], s[10:11], v0, s0, v[10:11]
	v_lshrrev_b32_e32 v12, 27, v12
	v_mad_i32_i24 v5, v1, s0, v5
	s_lshl_b32 s38, s2, 1
	v_add_u32_e32 v14, v13, v12
	v_lshl_add_u64 v[0:1], v[4:5], 0, s[38:39]
	v_ashrrev_i32_e32 v3, 31, v2
	v_ashrrev_i32_e32 v12, 5, v14
	v_and_b32_e32 v14, 0x1fffffe0, v14
	v_lshl_add_u64 v[0:1], v[2:3], 1, v[0:1]
	v_add_u32_e32 v3, 0x200, v8
	v_sub_u32_e32 v13, v13, v14
	v_ashrrev_i32_e32 v2, 31, v3
	v_lshlrev_b32_e32 v14, 3, v13
	v_ashrrev_i32_e32 v13, 31, v12
	v_lshrrev_b32_e32 v2, 27, v2
	v_lshl_add_u64 v[12:13], s[8:9], 0, v[12:13]
	v_add_u32_e32 v4, v3, v2
	v_mad_u64_u32 v[16:17], s[10:11], v12, s0, v[10:11]
	v_ashrrev_i32_e32 v2, 5, v4
	v_and_b32_e32 v4, 0x1fffffe0, v4
	v_mad_i32_i24 v17, v13, s0, v17
	v_sub_u32_e32 v3, v3, v4
	v_lshl_add_u64 v[12:13], v[16:17], 0, s[38:39]
	v_ashrrev_i32_e32 v15, 31, v14
	v_add_u32_e32 v8, 0x600, v8
	v_lshlrev_b32_e32 v4, 3, v3
	v_ashrrev_i32_e32 v3, 31, v2
	v_lshl_add_u64 v[12:13], v[14:15], 1, v[12:13]
	v_ashrrev_i32_e32 v14, 31, v8
	v_lshl_add_u64 v[2:3], s[8:9], 0, v[2:3]
	v_lshrrev_b32_e32 v14, 27, v14
	v_mad_u64_u32 v[6:7], s[10:11], v2, s0, v[10:11]
	v_add_u32_e32 v15, v8, v14
	v_mad_i32_i24 v7, v3, s0, v7
	v_ashrrev_i32_e32 v14, 5, v15
	v_and_b32_e32 v15, 0x1fffffe0, v15
	v_add_co_u32_e32 v0, vcc, s1, v0
	v_lshl_add_u64 v[2:3], v[6:7], 0, s[38:39]
	v_ashrrev_i32_e32 v5, 31, v4
	v_sub_u32_e32 v8, v8, v15
	v_ashrrev_i32_e32 v15, 31, v14
	v_addc_co_u32_e32 v1, vcc, 0, v1, vcc
	v_lshl_add_u64 v[2:3], v[4:5], 1, v[2:3]
	v_lshl_add_u64 v[14:15], s[8:9], 0, v[14:15]
	v_add_co_u32_e32 v4, vcc, s1, v2
	v_mad_u64_u32 v[10:11], s[8:9], v14, s0, v[10:11]
	s_nop 0
	v_addc_co_u32_e32 v5, vcc, 0, v3, vcc
	v_lshlrev_b32_e32 v16, 3, v8
	v_mad_i32_i24 v11, v15, s0, v11
	v_add_co_u32_e32 v12, vcc, s1, v12
	v_lshl_add_u64 v[10:11], v[10:11], 0, s[38:39]
	v_ashrrev_i32_e32 v17, 31, v16
	v_addc_co_u32_e32 v13, vcc, 0, v13, vcc
	v_lshl_add_u64 v[10:11], v[16:17], 1, v[10:11]
	v_add_co_u32_e32 v10, vcc, 0x7a00000, v10
	global_load_dwordx4 v[0:3], v[0:1], off offset:2048
	s_nop 0
	global_load_dwordx4 v[4:7], v[4:5], off offset:2048
	v_addc_co_u32_e32 v11, vcc, 0, v11, vcc
	global_load_dwordx4 v[12:15], v[12:13], off offset:2048
	s_nop 0
	global_load_dwordx4 v[16:19], v[10:11], off offset:2048
